# proj GEMM mainloop switched to v_mfma_f32_16x16x32_bf16 (same bf16 operands, f32 accumulate) with A-fragment ring + rewritten accumulator staging for the 16x16 layout
# speedup vs baseline: 1.0143x; 1.0143x over previous
.LBB0_160:
	s_lshl_b32 s58, s13, 8
	v_readlane_b32 s10, v255, 49
	s_lshl_b32 s10, s10, 8
	v_readlane_b32 s42, v255, 13
	v_readlane_b32 s43, v255, 14
	s_mov_b32 s44, s22
	s_mov_b32 s45, s23
	s_mov_b32 s47, m0
	v_readfirstlane_b32 s46, v195
	v_add_lshl_u32 v1, s58, v155, 10
	v_add_lshl_u32 v3, s10, v155, 10
	s_lshl_b32 s46, s46, 4
	s_and_b32 s46, s46, 0xfffffc00
	v_or_b32_e32 v248, v1, v168
	v_add_u32_e32 v249, v1, v183
	v_add_u32_e32 v220, v1, v184
	v_add_u32_e32 v221, v1, v185
	v_or_b32_e32 v222, v3, v168
	v_add_u32_e32 v234, v3, v183
	v_add_u32_e32 v239, v3, v184
	v_add_u32_e32 v252, v3, v185
	v_lshlrev_b32_e32 v248, 1, v248
	v_lshlrev_b32_e32 v249, 1, v249
	v_lshlrev_b32_e32 v220, 1, v220
	v_lshlrev_b32_e32 v221, 1, v221
	v_lshlrev_b32_e32 v222, 1, v222
	v_lshlrev_b32_e32 v234, 1, v234
	v_lshlrev_b32_e32 v239, 1, v239
	v_lshlrev_b32_e32 v252, 1, v252
	v_and_b32_e32 v4, 15, v195
	v_lshrrev_b32_e32 v5, 8, v195
	v_lshl_add_u32 v5, v5, 7, v4
	v_lshlrev_b32_e32 v5, 7, v5
	v_bfe_u32 v6, v195, 4, 2
	v_bfe_u32 v7, v195, 1, 3
	v_xor_b32_e32 v6, v6, v7
	v_lshlrev_b32_e32 v6, 4, v6
	v_or_b32_e32 v139, v5, v6
	v_xor_b32_e32 v141, 64, v139
	v_bfe_u32 v7, v195, 6, 2
	v_lshl_add_u32 v7, v7, 6, v4
	v_lshlrev_b32_e32 v7, 7, v7
	v_or_b32_e32 v143, v7, v6
	v_xor_b32_e32 v152, 64, v143
	s_mov_b32 m0, s46
	s_nop 0
	global_load_lds_dwordx4 v248, s[42:43]
	s_add_u32 m0, s46, 0x8000
	s_nop 0
	global_load_lds_dwordx4 v222, s[44:45]
	s_add_u32 m0, s46, 0x2000
	s_nop 0
	global_load_lds_dwordx4 v249, s[42:43]
	s_add_u32 m0, s46, 0xa000
	s_nop 0
	global_load_lds_dwordx4 v234, s[44:45]
	s_add_u32 m0, s46, 0x4000
	s_nop 0
	global_load_lds_dwordx4 v220, s[42:43]
	s_add_u32 m0, s46, 0xc000
	s_nop 0
	global_load_lds_dwordx4 v239, s[44:45]
	s_add_u32 m0, s46, 0x6000
	s_nop 0
	global_load_lds_dwordx4 v221, s[42:43]
	s_add_u32 m0, s46, 0xe000
	s_nop 0
	global_load_lds_dwordx4 v252, s[44:45]
	s_add_u32 s42, s42, 0x80
	s_addc_u32 s43, s43, 0
	s_add_u32 s44, s44, 0x80
	s_addc_u32 s45, s45, 0
	s_waitcnt vmcnt(0)
	s_barrier
	ds_read_b128 v[156:159], v143 offset:32768
	ds_read_b128 v[160:163], v143 offset:34816
	ds_read_b128 v[164:167], v143 offset:36864
	ds_read_b128 v[202:205], v143 offset:38912
	ds_read_b128 v[128:131], v139
	ds_read_b128 v[132:135], v139 offset:2048
	ds_read_b128 v[144:147], v139 offset:4096
	s_add_u32 m0, s46, 0x10000
	s_nop 0
	global_load_lds_dwordx4 v248, s[42:43]
	s_add_u32 m0, s46, 0x18000
	s_nop 0
	global_load_lds_dwordx4 v222, s[44:45]
	s_add_u32 m0, s46, 0x12000
	s_nop 0
	global_load_lds_dwordx4 v249, s[42:43]
	s_add_u32 m0, s46, 0x1a000
	s_nop 0
	global_load_lds_dwordx4 v234, s[44:45]
	s_add_u32 m0, s46, 0x14000
	s_nop 0
	global_load_lds_dwordx4 v220, s[42:43]
	s_add_u32 m0, s46, 0x1c000
	s_nop 0
	global_load_lds_dwordx4 v239, s[44:45]
	s_add_u32 m0, s46, 0x16000
	s_nop 0
	global_load_lds_dwordx4 v221, s[42:43]
	s_add_u32 m0, s46, 0x1e000
	s_nop 0
	global_load_lds_dwordx4 v252, s[44:45]
	s_add_u32 s42, s42, 0x80
	s_addc_u32 s43, s43, 0
	s_add_u32 s44, s44, 0x80
	s_addc_u32 s45, s45, 0
	s_waitcnt lgkmcnt(2)
	v_mfma_f32_16x16x32_bf16 v[0:3], v[128:131], v[156:159], 0
	ds_read_b128 v[148:151], v139 offset:6144
	v_mfma_f32_16x16x32_bf16 v[4:7], v[128:131], v[160:163], 0
	ds_read_b128 v[212:215], v152 offset:32768
	v_mfma_f32_16x16x32_bf16 v[8:11], v[128:131], v[164:167], 0
	v_mfma_f32_16x16x32_bf16 v[12:15], v[128:131], v[202:205], 0
	s_waitcnt lgkmcnt(3)
	v_mfma_f32_16x16x32_bf16 v[16:19], v[132:135], v[156:159], 0
	ds_read_b128 v[128:131], v139 offset:8192
	v_mfma_f32_16x16x32_bf16 v[20:23], v[132:135], v[160:163], 0
	ds_read_b128 v[216:219], v152 offset:34816
	v_mfma_f32_16x16x32_bf16 v[24:27], v[132:135], v[164:167], 0
	v_mfma_f32_16x16x32_bf16 v[28:31], v[132:135], v[202:205], 0
	s_waitcnt lgkmcnt(4)
	v_mfma_f32_16x16x32_bf16 v[32:35], v[144:147], v[156:159], 0
	ds_read_b128 v[132:135], v139 offset:10240
	v_mfma_f32_16x16x32_bf16 v[36:39], v[144:147], v[160:163], 0
	ds_read_b128 v[240:243], v152 offset:36864
	v_mfma_f32_16x16x32_bf16 v[40:43], v[144:147], v[164:167], 0
	v_mfma_f32_16x16x32_bf16 v[44:47], v[144:147], v[202:205], 0
	s_waitcnt lgkmcnt(5)
	v_mfma_f32_16x16x32_bf16 v[48:51], v[148:151], v[156:159], 0
	ds_read_b128 v[144:147], v139 offset:12288
	v_mfma_f32_16x16x32_bf16 v[52:55], v[148:151], v[160:163], 0
	ds_read_b128 v[244:247], v152 offset:38912
	v_mfma_f32_16x16x32_bf16 v[56:59], v[148:151], v[164:167], 0
	v_mfma_f32_16x16x32_bf16 v[60:63], v[148:151], v[202:205], 0
	s_waitcnt lgkmcnt(5)
	v_mfma_f32_16x16x32_bf16 v[64:67], v[128:131], v[156:159], 0
	ds_read_b128 v[148:151], v139 offset:14336
	v_mfma_f32_16x16x32_bf16 v[68:71], v[128:131], v[160:163], 0
	v_mfma_f32_16x16x32_bf16 v[72:75], v[128:131], v[164:167], 0
	v_mfma_f32_16x16x32_bf16 v[76:79], v[128:131], v[202:205], 0
	s_waitcnt lgkmcnt(4)
	v_mfma_f32_16x16x32_bf16 v[80:83], v[132:135], v[156:159], 0
	ds_read_b128 v[128:131], v141
	v_mfma_f32_16x16x32_bf16 v[84:87], v[132:135], v[160:163], 0
	v_mfma_f32_16x16x32_bf16 v[88:91], v[132:135], v[164:167], 0
	v_mfma_f32_16x16x32_bf16 v[92:95], v[132:135], v[202:205], 0
	s_waitcnt lgkmcnt(3)
	v_mfma_f32_16x16x32_bf16 v[96:99], v[144:147], v[156:159], 0
	ds_read_b128 v[132:135], v141 offset:2048
	v_mfma_f32_16x16x32_bf16 v[100:103], v[144:147], v[160:163], 0
	v_mfma_f32_16x16x32_bf16 v[104:107], v[144:147], v[164:167], 0
	v_mfma_f32_16x16x32_bf16 v[108:111], v[144:147], v[202:205], 0
	s_waitcnt lgkmcnt(2)
	v_mfma_f32_16x16x32_bf16 v[112:115], v[148:151], v[156:159], 0
	ds_read_b128 v[144:147], v141 offset:4096
	v_mfma_f32_16x16x32_bf16 v[116:119], v[148:151], v[160:163], 0
	v_mfma_f32_16x16x32_bf16 v[120:123], v[148:151], v[164:167], 0
	v_mfma_f32_16x16x32_bf16 v[124:127], v[148:151], v[202:205], 0
	s_waitcnt lgkmcnt(2)
	v_mfma_f32_16x16x32_bf16 v[0:3], v[128:131], v[212:215], v[0:3]
	ds_read_b128 v[148:151], v141 offset:6144
	v_mfma_f32_16x16x32_bf16 v[4:7], v[128:131], v[216:219], v[4:7]
	v_mfma_f32_16x16x32_bf16 v[8:11], v[128:131], v[240:243], v[8:11]
	v_mfma_f32_16x16x32_bf16 v[12:15], v[128:131], v[244:247], v[12:15]
	s_waitcnt lgkmcnt(2)
	v_mfma_f32_16x16x32_bf16 v[16:19], v[132:135], v[212:215], v[16:19]
	ds_read_b128 v[128:131], v141 offset:8192
	v_mfma_f32_16x16x32_bf16 v[20:23], v[132:135], v[216:219], v[20:23]
	v_mfma_f32_16x16x32_bf16 v[24:27], v[132:135], v[240:243], v[24:27]
	v_mfma_f32_16x16x32_bf16 v[28:31], v[132:135], v[244:247], v[28:31]
	s_waitcnt lgkmcnt(2)
	v_mfma_f32_16x16x32_bf16 v[32:35], v[144:147], v[212:215], v[32:35]
	ds_read_b128 v[132:135], v141 offset:10240
	v_mfma_f32_16x16x32_bf16 v[36:39], v[144:147], v[216:219], v[36:39]
	v_mfma_f32_16x16x32_bf16 v[40:43], v[144:147], v[240:243], v[40:43]
	v_mfma_f32_16x16x32_bf16 v[44:47], v[144:147], v[244:247], v[44:47]
	s_waitcnt lgkmcnt(2)
	v_mfma_f32_16x16x32_bf16 v[48:51], v[148:151], v[212:215], v[48:51]
	ds_read_b128 v[144:147], v141 offset:12288
	v_mfma_f32_16x16x32_bf16 v[52:55], v[148:151], v[216:219], v[52:55]
	v_mfma_f32_16x16x32_bf16 v[56:59], v[148:151], v[240:243], v[56:59]
	v_mfma_f32_16x16x32_bf16 v[60:63], v[148:151], v[244:247], v[60:63]
	s_waitcnt lgkmcnt(2)
	v_mfma_f32_16x16x32_bf16 v[64:67], v[128:131], v[212:215], v[64:67]
	ds_read_b128 v[148:151], v141 offset:14336
	v_mfma_f32_16x16x32_bf16 v[68:71], v[128:131], v[216:219], v[68:71]
	v_mfma_f32_16x16x32_bf16 v[72:75], v[128:131], v[240:243], v[72:75]
	v_mfma_f32_16x16x32_bf16 v[76:79], v[128:131], v[244:247], v[76:79]
	s_waitcnt lgkmcnt(2)
	v_mfma_f32_16x16x32_bf16 v[80:83], v[132:135], v[212:215], v[80:83]
	v_mfma_f32_16x16x32_bf16 v[84:87], v[132:135], v[216:219], v[84:87]
	v_mfma_f32_16x16x32_bf16 v[88:91], v[132:135], v[240:243], v[88:91]
	v_mfma_f32_16x16x32_bf16 v[92:95], v[132:135], v[244:247], v[92:95]
	s_waitcnt lgkmcnt(0)
	s_waitcnt vmcnt(0)
	s_barrier
	v_xor_b32_e32 v139, 0x10000, v139
	v_xor_b32_e32 v141, 0x10000, v141
	v_xor_b32_e32 v143, 0x10000, v143
	v_xor_b32_e32 v152, 0x10000, v152
	v_mfma_f32_16x16x32_bf16 v[96:99], v[144:147], v[212:215], v[96:99]
	ds_read_b128 v[128:131], v139
	ds_read_b128 v[132:135], v139 offset:2048
	s_mov_b32 m0, s46
	v_mfma_f32_16x16x32_bf16 v[100:103], v[144:147], v[216:219], v[100:103]
	global_load_lds_dwordx4 v248, s[42:43]
	v_mfma_f32_16x16x32_bf16 v[104:107], v[144:147], v[240:243], v[104:107]
	ds_read_b128 v[156:159], v143 offset:32768
	ds_read_b128 v[160:163], v143 offset:34816
	s_add_u32 m0, s46, 0x8000
	v_mfma_f32_16x16x32_bf16 v[108:111], v[144:147], v[244:247], v[108:111]
	global_load_lds_dwordx4 v222, s[44:45]
	v_mfma_f32_16x16x32_bf16 v[112:115], v[148:151], v[212:215], v[112:115]
	ds_read_b128 v[144:147], v139 offset:4096
	s_add_u32 m0, s46, 0x2000
	v_mfma_f32_16x16x32_bf16 v[116:119], v[148:151], v[216:219], v[116:119]
	global_load_lds_dwordx4 v249, s[42:43]
	ds_read_b128 v[164:167], v143 offset:36864
	ds_read_b128 v[202:205], v143 offset:38912
	v_mfma_f32_16x16x32_bf16 v[120:123], v[148:151], v[240:243], v[120:123]
	s_add_u32 m0, s46, 0xa000
	v_mfma_f32_16x16x32_bf16 v[124:127], v[148:151], v[244:247], v[124:127]
	global_load_lds_dwordx4 v234, s[44:45]
	s_waitcnt lgkmcnt(4)
	v_mfma_f32_16x16x32_bf16 v[0:3], v[128:131], v[156:159], v[0:3]
	ds_read_b128 v[148:151], v139 offset:6144
	s_waitcnt lgkmcnt(4)
	v_mfma_f32_16x16x32_bf16 v[4:7], v[128:131], v[160:163], v[4:7]
	ds_read_b128 v[212:215], v152 offset:32768
	s_waitcnt lgkmcnt(3)
	v_mfma_f32_16x16x32_bf16 v[8:11], v[128:131], v[164:167], v[8:11]
	s_waitcnt lgkmcnt(2)
	v_mfma_f32_16x16x32_bf16 v[12:15], v[128:131], v[202:205], v[12:15]
	v_mfma_f32_16x16x32_bf16 v[16:19], v[132:135], v[156:159], v[16:19]
	ds_read_b128 v[128:131], v139 offset:8192
	v_mfma_f32_16x16x32_bf16 v[20:23], v[132:135], v[160:163], v[20:23]
	ds_read_b128 v[216:219], v152 offset:34816
	v_mfma_f32_16x16x32_bf16 v[24:27], v[132:135], v[164:167], v[24:27]
	v_mfma_f32_16x16x32_bf16 v[28:31], v[132:135], v[202:205], v[28:31]
	v_mfma_f32_16x16x32_bf16 v[32:35], v[144:147], v[156:159], v[32:35]
	ds_read_b128 v[132:135], v139 offset:10240
	v_mfma_f32_16x16x32_bf16 v[36:39], v[144:147], v[160:163], v[36:39]
	ds_read_b128 v[240:243], v152 offset:36864
	v_mfma_f32_16x16x32_bf16 v[40:43], v[144:147], v[164:167], v[40:43]
	s_add_u32 m0, s46, 0x4000
	v_mfma_f32_16x16x32_bf16 v[44:47], v[144:147], v[202:205], v[44:47]
	global_load_lds_dwordx4 v220, s[42:43]
	s_waitcnt lgkmcnt(5)
	v_mfma_f32_16x16x32_bf16 v[48:51], v[148:151], v[156:159], v[48:51]
	ds_read_b128 v[144:147], v139 offset:12288
	v_mfma_f32_16x16x32_bf16 v[52:55], v[148:151], v[160:163], v[52:55]
	ds_read_b128 v[244:247], v152 offset:38912
	v_mfma_f32_16x16x32_bf16 v[56:59], v[148:151], v[164:167], v[56:59]
	s_add_u32 m0, s46, 0xc000
	v_mfma_f32_16x16x32_bf16 v[60:63], v[148:151], v[202:205], v[60:63]
	global_load_lds_dwordx4 v239, s[44:45]
	s_waitcnt lgkmcnt(5)
	v_mfma_f32_16x16x32_bf16 v[64:67], v[128:131], v[156:159], v[64:67]
	ds_read_b128 v[148:151], v139 offset:14336
	v_mfma_f32_16x16x32_bf16 v[68:71], v[128:131], v[160:163], v[68:71]
	v_mfma_f32_16x16x32_bf16 v[72:75], v[128:131], v[164:167], v[72:75]
	s_add_u32 m0, s46, 0x6000
	v_mfma_f32_16x16x32_bf16 v[76:79], v[128:131], v[202:205], v[76:79]
	global_load_lds_dwordx4 v221, s[42:43]
	s_waitcnt lgkmcnt(4)
	v_mfma_f32_16x16x32_bf16 v[80:83], v[132:135], v[156:159], v[80:83]
	ds_read_b128 v[128:131], v141
	v_mfma_f32_16x16x32_bf16 v[84:87], v[132:135], v[160:163], v[84:87]
	v_mfma_f32_16x16x32_bf16 v[88:91], v[132:135], v[164:167], v[88:91]
	s_add_u32 m0, s46, 0xe000
	v_mfma_f32_16x16x32_bf16 v[92:95], v[132:135], v[202:205], v[92:95]
	global_load_lds_dwordx4 v252, s[44:45]
	s_add_u32 s42, s42, 0x80
	s_addc_u32 s43, s43, 0
	s_add_u32 s44, s44, 0x80
	s_addc_u32 s45, s45, 0
	s_waitcnt lgkmcnt(3)
	v_mfma_f32_16x16x32_bf16 v[96:99], v[144:147], v[156:159], v[96:99]
	ds_read_b128 v[132:135], v141 offset:2048
	v_mfma_f32_16x16x32_bf16 v[100:103], v[144:147], v[160:163], v[100:103]
	v_mfma_f32_16x16x32_bf16 v[104:107], v[144:147], v[164:167], v[104:107]
	v_mfma_f32_16x16x32_bf16 v[108:111], v[144:147], v[202:205], v[108:111]
	s_waitcnt lgkmcnt(2)
	v_mfma_f32_16x16x32_bf16 v[112:115], v[148:151], v[156:159], v[112:115]
	ds_read_b128 v[144:147], v141 offset:4096
	v_mfma_f32_16x16x32_bf16 v[116:119], v[148:151], v[160:163], v[116:119]
	v_mfma_f32_16x16x32_bf16 v[120:123], v[148:151], v[164:167], v[120:123]
	v_mfma_f32_16x16x32_bf16 v[124:127], v[148:151], v[202:205], v[124:127]
	s_waitcnt lgkmcnt(2)
	v_mfma_f32_16x16x32_bf16 v[0:3], v[128:131], v[212:215], v[0:3]
	ds_read_b128 v[148:151], v141 offset:6144
	v_mfma_f32_16x16x32_bf16 v[4:7], v[128:131], v[216:219], v[4:7]
	v_mfma_f32_16x16x32_bf16 v[8:11], v[128:131], v[240:243], v[8:11]
	v_mfma_f32_16x16x32_bf16 v[12:15], v[128:131], v[244:247], v[12:15]
	s_waitcnt lgkmcnt(2)
	v_mfma_f32_16x16x32_bf16 v[16:19], v[132:135], v[212:215], v[16:19]
	ds_read_b128 v[128:131], v141 offset:8192
	v_mfma_f32_16x16x32_bf16 v[20:23], v[132:135], v[216:219], v[20:23]
	v_mfma_f32_16x16x32_bf16 v[24:27], v[132:135], v[240:243], v[24:27]
	v_mfma_f32_16x16x32_bf16 v[28:31], v[132:135], v[244:247], v[28:31]
	s_waitcnt lgkmcnt(2)
	v_mfma_f32_16x16x32_bf16 v[32:35], v[144:147], v[212:215], v[32:35]
	ds_read_b128 v[132:135], v141 offset:10240
	v_mfma_f32_16x16x32_bf16 v[36:39], v[144:147], v[216:219], v[36:39]
	v_mfma_f32_16x16x32_bf16 v[40:43], v[144:147], v[240:243], v[40:43]
	v_mfma_f32_16x16x32_bf16 v[44:47], v[144:147], v[244:247], v[44:47]
	s_waitcnt lgkmcnt(2)
	v_mfma_f32_16x16x32_bf16 v[48:51], v[148:151], v[212:215], v[48:51]
	ds_read_b128 v[144:147], v141 offset:12288
	v_mfma_f32_16x16x32_bf16 v[52:55], v[148:151], v[216:219], v[52:55]
	v_mfma_f32_16x16x32_bf16 v[56:59], v[148:151], v[240:243], v[56:59]
	v_mfma_f32_16x16x32_bf16 v[60:63], v[148:151], v[244:247], v[60:63]
	s_waitcnt lgkmcnt(2)
	v_mfma_f32_16x16x32_bf16 v[64:67], v[128:131], v[212:215], v[64:67]
	ds_read_b128 v[148:151], v141 offset:14336
	v_mfma_f32_16x16x32_bf16 v[68:71], v[128:131], v[216:219], v[68:71]
	v_mfma_f32_16x16x32_bf16 v[72:75], v[128:131], v[240:243], v[72:75]
	v_mfma_f32_16x16x32_bf16 v[76:79], v[128:131], v[244:247], v[76:79]
	s_waitcnt lgkmcnt(2)
	v_mfma_f32_16x16x32_bf16 v[80:83], v[132:135], v[212:215], v[80:83]
	v_mfma_f32_16x16x32_bf16 v[84:87], v[132:135], v[216:219], v[84:87]
	v_mfma_f32_16x16x32_bf16 v[88:91], v[132:135], v[240:243], v[88:91]
	v_mfma_f32_16x16x32_bf16 v[92:95], v[132:135], v[244:247], v[92:95]
	s_waitcnt lgkmcnt(0)
	s_waitcnt vmcnt(0)
	s_barrier
	v_xor_b32_e32 v139, 0x10000, v139
	v_xor_b32_e32 v141, 0x10000, v141
	v_xor_b32_e32 v143, 0x10000, v143
	v_xor_b32_e32 v152, 0x10000, v152
	v_mfma_f32_16x16x32_bf16 v[96:99], v[144:147], v[212:215], v[96:99]
	ds_read_b128 v[128:131], v139
	ds_read_b128 v[132:135], v139 offset:2048
	s_add_u32 m0, s46, 0x10000
	v_mfma_f32_16x16x32_bf16 v[100:103], v[144:147], v[216:219], v[100:103]
	global_load_lds_dwordx4 v248, s[42:43]
	v_mfma_f32_16x16x32_bf16 v[104:107], v[144:147], v[240:243], v[104:107]
	ds_read_b128 v[156:159], v143 offset:32768
	ds_read_b128 v[160:163], v143 offset:34816
	s_add_u32 m0, s46, 0x18000
	v_mfma_f32_16x16x32_bf16 v[108:111], v[144:147], v[244:247], v[108:111]
	global_load_lds_dwordx4 v222, s[44:45]
	v_mfma_f32_16x16x32_bf16 v[112:115], v[148:151], v[212:215], v[112:115]
	ds_read_b128 v[144:147], v139 offset:4096
	s_add_u32 m0, s46, 0x12000
	v_mfma_f32_16x16x32_bf16 v[116:119], v[148:151], v[216:219], v[116:119]
	global_load_lds_dwordx4 v249, s[42:43]
	ds_read_b128 v[164:167], v143 offset:36864
	ds_read_b128 v[202:205], v143 offset:38912
	v_mfma_f32_16x16x32_bf16 v[120:123], v[148:151], v[240:243], v[120:123]
	s_add_u32 m0, s46, 0x1a000
	v_mfma_f32_16x16x32_bf16 v[124:127], v[148:151], v[244:247], v[124:127]
	global_load_lds_dwordx4 v234, s[44:45]
	s_waitcnt lgkmcnt(4)
	v_mfma_f32_16x16x32_bf16 v[0:3], v[128:131], v[156:159], v[0:3]
	ds_read_b128 v[148:151], v139 offset:6144
	s_waitcnt lgkmcnt(4)
	v_mfma_f32_16x16x32_bf16 v[4:7], v[128:131], v[160:163], v[4:7]
	ds_read_b128 v[212:215], v152 offset:32768
	s_waitcnt lgkmcnt(3)
	v_mfma_f32_16x16x32_bf16 v[8:11], v[128:131], v[164:167], v[8:11]
	s_waitcnt lgkmcnt(2)
	v_mfma_f32_16x16x32_bf16 v[12:15], v[128:131], v[202:205], v[12:15]
	v_mfma_f32_16x16x32_bf16 v[16:19], v[132:135], v[156:159], v[16:19]
	ds_read_b128 v[128:131], v139 offset:8192
	v_mfma_f32_16x16x32_bf16 v[20:23], v[132:135], v[160:163], v[20:23]
	ds_read_b128 v[216:219], v152 offset:34816
	v_mfma_f32_16x16x32_bf16 v[24:27], v[132:135], v[164:167], v[24:27]
	v_mfma_f32_16x16x32_bf16 v[28:31], v[132:135], v[202:205], v[28:31]
	v_mfma_f32_16x16x32_bf16 v[32:35], v[144:147], v[156:159], v[32:35]
	ds_read_b128 v[132:135], v139 offset:10240
	v_mfma_f32_16x16x32_bf16 v[36:39], v[144:147], v[160:163], v[36:39]
	ds_read_b128 v[240:243], v152 offset:36864
	v_mfma_f32_16x16x32_bf16 v[40:43], v[144:147], v[164:167], v[40:43]
	s_add_u32 m0, s46, 0x14000
	v_mfma_f32_16x16x32_bf16 v[44:47], v[144:147], v[202:205], v[44:47]
	global_load_lds_dwordx4 v220, s[42:43]
	s_waitcnt lgkmcnt(5)
	v_mfma_f32_16x16x32_bf16 v[48:51], v[148:151], v[156:159], v[48:51]
	ds_read_b128 v[144:147], v139 offset:12288
	v_mfma_f32_16x16x32_bf16 v[52:55], v[148:151], v[160:163], v[52:55]
	ds_read_b128 v[244:247], v152 offset:38912
	v_mfma_f32_16x16x32_bf16 v[56:59], v[148:151], v[164:167], v[56:59]
	s_add_u32 m0, s46, 0x1c000
	v_mfma_f32_16x16x32_bf16 v[60:63], v[148:151], v[202:205], v[60:63]
	global_load_lds_dwordx4 v239, s[44:45]
	s_waitcnt lgkmcnt(5)
	v_mfma_f32_16x16x32_bf16 v[64:67], v[128:131], v[156:159], v[64:67]
	ds_read_b128 v[148:151], v139 offset:14336
	v_mfma_f32_16x16x32_bf16 v[68:71], v[128:131], v[160:163], v[68:71]
	v_mfma_f32_16x16x32_bf16 v[72:75], v[128:131], v[164:167], v[72:75]
	s_add_u32 m0, s46, 0x16000
	v_mfma_f32_16x16x32_bf16 v[76:79], v[128:131], v[202:205], v[76:79]
	global_load_lds_dwordx4 v221, s[42:43]
	s_waitcnt lgkmcnt(4)
	v_mfma_f32_16x16x32_bf16 v[80:83], v[132:135], v[156:159], v[80:83]
	ds_read_b128 v[128:131], v141
	v_mfma_f32_16x16x32_bf16 v[84:87], v[132:135], v[160:163], v[84:87]
	v_mfma_f32_16x16x32_bf16 v[88:91], v[132:135], v[164:167], v[88:91]
	s_add_u32 m0, s46, 0x1e000
	v_mfma_f32_16x16x32_bf16 v[92:95], v[132:135], v[202:205], v[92:95]
	global_load_lds_dwordx4 v252, s[44:45]
	s_add_u32 s42, s42, 0x80
	s_addc_u32 s43, s43, 0
	s_add_u32 s44, s44, 0x80
	s_addc_u32 s45, s45, 0
	s_waitcnt lgkmcnt(3)
	v_mfma_f32_16x16x32_bf16 v[96:99], v[144:147], v[156:159], v[96:99]
	ds_read_b128 v[132:135], v141 offset:2048
	v_mfma_f32_16x16x32_bf16 v[100:103], v[144:147], v[160:163], v[100:103]
	v_mfma_f32_16x16x32_bf16 v[104:107], v[144:147], v[164:167], v[104:107]
	v_mfma_f32_16x16x32_bf16 v[108:111], v[144:147], v[202:205], v[108:111]
	s_waitcnt lgkmcnt(2)
	v_mfma_f32_16x16x32_bf16 v[112:115], v[148:151], v[156:159], v[112:115]
	ds_read_b128 v[144:147], v141 offset:4096
	v_mfma_f32_16x16x32_bf16 v[116:119], v[148:151], v[160:163], v[116:119]
	v_mfma_f32_16x16x32_bf16 v[120:123], v[148:151], v[164:167], v[120:123]
	v_mfma_f32_16x16x32_bf16 v[124:127], v[148:151], v[202:205], v[124:127]
	s_waitcnt lgkmcnt(2)
	v_mfma_f32_16x16x32_bf16 v[0:3], v[128:131], v[212:215], v[0:3]
	ds_read_b128 v[148:151], v141 offset:6144
	v_mfma_f32_16x16x32_bf16 v[4:7], v[128:131], v[216:219], v[4:7]
	v_mfma_f32_16x16x32_bf16 v[8:11], v[128:131], v[240:243], v[8:11]
	v_mfma_f32_16x16x32_bf16 v[12:15], v[128:131], v[244:247], v[12:15]
	s_waitcnt lgkmcnt(2)
	v_mfma_f32_16x16x32_bf16 v[16:19], v[132:135], v[212:215], v[16:19]
	ds_read_b128 v[128:131], v141 offset:8192
	v_mfma_f32_16x16x32_bf16 v[20:23], v[132:135], v[216:219], v[20:23]
	v_mfma_f32_16x16x32_bf16 v[24:27], v[132:135], v[240:243], v[24:27]
	v_mfma_f32_16x16x32_bf16 v[28:31], v[132:135], v[244:247], v[28:31]
	s_waitcnt lgkmcnt(2)
	v_mfma_f32_16x16x32_bf16 v[32:35], v[144:147], v[212:215], v[32:35]
	ds_read_b128 v[132:135], v141 offset:10240
	v_mfma_f32_16x16x32_bf16 v[36:39], v[144:147], v[216:219], v[36:39]
	v_mfma_f32_16x16x32_bf16 v[40:43], v[144:147], v[240:243], v[40:43]
	v_mfma_f32_16x16x32_bf16 v[44:47], v[144:147], v[244:247], v[44:47]
	s_waitcnt lgkmcnt(2)
	v_mfma_f32_16x16x32_bf16 v[48:51], v[148:151], v[212:215], v[48:51]
	ds_read_b128 v[144:147], v141 offset:12288
	v_mfma_f32_16x16x32_bf16 v[52:55], v[148:151], v[216:219], v[52:55]
	v_mfma_f32_16x16x32_bf16 v[56:59], v[148:151], v[240:243], v[56:59]
	v_mfma_f32_16x16x32_bf16 v[60:63], v[148:151], v[244:247], v[60:63]
	s_waitcnt lgkmcnt(2)
	v_mfma_f32_16x16x32_bf16 v[64:67], v[128:131], v[212:215], v[64:67]
	ds_read_b128 v[148:151], v141 offset:14336
	v_mfma_f32_16x16x32_bf16 v[68:71], v[128:131], v[216:219], v[68:71]
	v_mfma_f32_16x16x32_bf16 v[72:75], v[128:131], v[240:243], v[72:75]
	v_mfma_f32_16x16x32_bf16 v[76:79], v[128:131], v[244:247], v[76:79]
	s_waitcnt lgkmcnt(2)
	v_mfma_f32_16x16x32_bf16 v[80:83], v[132:135], v[212:215], v[80:83]
	v_mfma_f32_16x16x32_bf16 v[84:87], v[132:135], v[216:219], v[84:87]
	v_mfma_f32_16x16x32_bf16 v[88:91], v[132:135], v[240:243], v[88:91]
	v_mfma_f32_16x16x32_bf16 v[92:95], v[132:135], v[244:247], v[92:95]
	s_waitcnt lgkmcnt(0)
	s_waitcnt vmcnt(0)
	s_barrier
	v_xor_b32_e32 v139, 0x10000, v139
	v_xor_b32_e32 v141, 0x10000, v141
	v_xor_b32_e32 v143, 0x10000, v143
	v_xor_b32_e32 v152, 0x10000, v152
	v_mfma_f32_16x16x32_bf16 v[96:99], v[144:147], v[212:215], v[96:99]
	ds_read_b128 v[128:131], v139
	ds_read_b128 v[132:135], v139 offset:2048
	s_mov_b32 m0, s46
	v_mfma_f32_16x16x32_bf16 v[100:103], v[144:147], v[216:219], v[100:103]
	global_load_lds_dwordx4 v248, s[42:43]
	v_mfma_f32_16x16x32_bf16 v[104:107], v[144:147], v[240:243], v[104:107]
	ds_read_b128 v[156:159], v143 offset:32768
	ds_read_b128 v[160:163], v143 offset:34816
	s_add_u32 m0, s46, 0x8000
	v_mfma_f32_16x16x32_bf16 v[108:111], v[144:147], v[244:247], v[108:111]
	global_load_lds_dwordx4 v222, s[44:45]
	v_mfma_f32_16x16x32_bf16 v[112:115], v[148:151], v[212:215], v[112:115]
	ds_read_b128 v[144:147], v139 offset:4096
	s_add_u32 m0, s46, 0x2000
	v_mfma_f32_16x16x32_bf16 v[116:119], v[148:151], v[216:219], v[116:119]
	global_load_lds_dwordx4 v249, s[42:43]
	ds_read_b128 v[164:167], v143 offset:36864
	ds_read_b128 v[202:205], v143 offset:38912
	v_mfma_f32_16x16x32_bf16 v[120:123], v[148:151], v[240:243], v[120:123]
	s_add_u32 m0, s46, 0xa000
	v_mfma_f32_16x16x32_bf16 v[124:127], v[148:151], v[244:247], v[124:127]
	global_load_lds_dwordx4 v234, s[44:45]
	s_waitcnt lgkmcnt(4)
	v_mfma_f32_16x16x32_bf16 v[0:3], v[128:131], v[156:159], v[0:3]
	ds_read_b128 v[148:151], v139 offset:6144
	s_waitcnt lgkmcnt(4)
	v_mfma_f32_16x16x32_bf16 v[4:7], v[128:131], v[160:163], v[4:7]
	ds_read_b128 v[212:215], v152 offset:32768
	s_waitcnt lgkmcnt(3)
	v_mfma_f32_16x16x32_bf16 v[8:11], v[128:131], v[164:167], v[8:11]
	s_waitcnt lgkmcnt(2)
	v_mfma_f32_16x16x32_bf16 v[12:15], v[128:131], v[202:205], v[12:15]
	v_mfma_f32_16x16x32_bf16 v[16:19], v[132:135], v[156:159], v[16:19]
	ds_read_b128 v[128:131], v139 offset:8192
	v_mfma_f32_16x16x32_bf16 v[20:23], v[132:135], v[160:163], v[20:23]
	ds_read_b128 v[216:219], v152 offset:34816
	v_mfma_f32_16x16x32_bf16 v[24:27], v[132:135], v[164:167], v[24:27]
	v_mfma_f32_16x16x32_bf16 v[28:31], v[132:135], v[202:205], v[28:31]
	v_mfma_f32_16x16x32_bf16 v[32:35], v[144:147], v[156:159], v[32:35]
	ds_read_b128 v[132:135], v139 offset:10240
	v_mfma_f32_16x16x32_bf16 v[36:39], v[144:147], v[160:163], v[36:39]
	ds_read_b128 v[240:243], v152 offset:36864
	v_mfma_f32_16x16x32_bf16 v[40:43], v[144:147], v[164:167], v[40:43]
	s_add_u32 m0, s46, 0x4000
	v_mfma_f32_16x16x32_bf16 v[44:47], v[144:147], v[202:205], v[44:47]
	global_load_lds_dwordx4 v220, s[42:43]
	s_waitcnt lgkmcnt(5)
	v_mfma_f32_16x16x32_bf16 v[48:51], v[148:151], v[156:159], v[48:51]
	ds_read_b128 v[144:147], v139 offset:12288
	v_mfma_f32_16x16x32_bf16 v[52:55], v[148:151], v[160:163], v[52:55]
	ds_read_b128 v[244:247], v152 offset:38912
	v_mfma_f32_16x16x32_bf16 v[56:59], v[148:151], v[164:167], v[56:59]
	s_add_u32 m0, s46, 0xc000
	v_mfma_f32_16x16x32_bf16 v[60:63], v[148:151], v[202:205], v[60:63]
	global_load_lds_dwordx4 v239, s[44:45]
	s_waitcnt lgkmcnt(5)
	v_mfma_f32_16x16x32_bf16 v[64:67], v[128:131], v[156:159], v[64:67]
	ds_read_b128 v[148:151], v139 offset:14336
	v_mfma_f32_16x16x32_bf16 v[68:71], v[128:131], v[160:163], v[68:71]
	v_mfma_f32_16x16x32_bf16 v[72:75], v[128:131], v[164:167], v[72:75]
	s_add_u32 m0, s46, 0x6000
	v_mfma_f32_16x16x32_bf16 v[76:79], v[128:131], v[202:205], v[76:79]
	global_load_lds_dwordx4 v221, s[42:43]
	s_waitcnt lgkmcnt(4)
	v_mfma_f32_16x16x32_bf16 v[80:83], v[132:135], v[156:159], v[80:83]
	ds_read_b128 v[128:131], v141
	v_mfma_f32_16x16x32_bf16 v[84:87], v[132:135], v[160:163], v[84:87]
	v_mfma_f32_16x16x32_bf16 v[88:91], v[132:135], v[164:167], v[88:91]
	s_add_u32 m0, s46, 0xe000
	v_mfma_f32_16x16x32_bf16 v[92:95], v[132:135], v[202:205], v[92:95]
	global_load_lds_dwordx4 v252, s[44:45]
	s_add_u32 s42, s42, 0x80
	s_addc_u32 s43, s43, 0
	s_add_u32 s44, s44, 0x80
	s_addc_u32 s45, s45, 0
	s_waitcnt lgkmcnt(3)
	v_mfma_f32_16x16x32_bf16 v[96:99], v[144:147], v[156:159], v[96:99]
	ds_read_b128 v[132:135], v141 offset:2048
	v_mfma_f32_16x16x32_bf16 v[100:103], v[144:147], v[160:163], v[100:103]
	v_mfma_f32_16x16x32_bf16 v[104:107], v[144:147], v[164:167], v[104:107]
	v_mfma_f32_16x16x32_bf16 v[108:111], v[144:147], v[202:205], v[108:111]
	s_waitcnt lgkmcnt(2)
	v_mfma_f32_16x16x32_bf16 v[112:115], v[148:151], v[156:159], v[112:115]
	ds_read_b128 v[144:147], v141 offset:4096
	v_mfma_f32_16x16x32_bf16 v[116:119], v[148:151], v[160:163], v[116:119]
	v_mfma_f32_16x16x32_bf16 v[120:123], v[148:151], v[164:167], v[120:123]
	v_mfma_f32_16x16x32_bf16 v[124:127], v[148:151], v[202:205], v[124:127]
	s_waitcnt lgkmcnt(2)
	v_mfma_f32_16x16x32_bf16 v[0:3], v[128:131], v[212:215], v[0:3]
	ds_read_b128 v[148:151], v141 offset:6144
	v_mfma_f32_16x16x32_bf16 v[4:7], v[128:131], v[216:219], v[4:7]
	v_mfma_f32_16x16x32_bf16 v[8:11], v[128:131], v[240:243], v[8:11]
	v_mfma_f32_16x16x32_bf16 v[12:15], v[128:131], v[244:247], v[12:15]
	s_waitcnt lgkmcnt(2)
	v_mfma_f32_16x16x32_bf16 v[16:19], v[132:135], v[212:215], v[16:19]
	ds_read_b128 v[128:131], v141 offset:8192
	v_mfma_f32_16x16x32_bf16 v[20:23], v[132:135], v[216:219], v[20:23]
	v_mfma_f32_16x16x32_bf16 v[24:27], v[132:135], v[240:243], v[24:27]
	v_mfma_f32_16x16x32_bf16 v[28:31], v[132:135], v[244:247], v[28:31]
	s_waitcnt lgkmcnt(2)
	v_mfma_f32_16x16x32_bf16 v[32:35], v[144:147], v[212:215], v[32:35]
	ds_read_b128 v[132:135], v141 offset:10240
	v_mfma_f32_16x16x32_bf16 v[36:39], v[144:147], v[216:219], v[36:39]
	v_mfma_f32_16x16x32_bf16 v[40:43], v[144:147], v[240:243], v[40:43]
	v_mfma_f32_16x16x32_bf16 v[44:47], v[144:147], v[244:247], v[44:47]
	s_waitcnt lgkmcnt(2)
	v_mfma_f32_16x16x32_bf16 v[48:51], v[148:151], v[212:215], v[48:51]
	ds_read_b128 v[144:147], v141 offset:12288
	v_mfma_f32_16x16x32_bf16 v[52:55], v[148:151], v[216:219], v[52:55]
	v_mfma_f32_16x16x32_bf16 v[56:59], v[148:151], v[240:243], v[56:59]
	v_mfma_f32_16x16x32_bf16 v[60:63], v[148:151], v[244:247], v[60:63]
	s_waitcnt lgkmcnt(2)
	v_mfma_f32_16x16x32_bf16 v[64:67], v[128:131], v[212:215], v[64:67]
	ds_read_b128 v[148:151], v141 offset:14336
	v_mfma_f32_16x16x32_bf16 v[68:71], v[128:131], v[216:219], v[68:71]
	v_mfma_f32_16x16x32_bf16 v[72:75], v[128:131], v[240:243], v[72:75]
	v_mfma_f32_16x16x32_bf16 v[76:79], v[128:131], v[244:247], v[76:79]
	s_waitcnt lgkmcnt(2)
	v_mfma_f32_16x16x32_bf16 v[80:83], v[132:135], v[212:215], v[80:83]
	v_mfma_f32_16x16x32_bf16 v[84:87], v[132:135], v[216:219], v[84:87]
	v_mfma_f32_16x16x32_bf16 v[88:91], v[132:135], v[240:243], v[88:91]
	v_mfma_f32_16x16x32_bf16 v[92:95], v[132:135], v[244:247], v[92:95]
	s_waitcnt lgkmcnt(0)
	s_waitcnt vmcnt(0)
	s_barrier
	v_xor_b32_e32 v139, 0x10000, v139
	v_xor_b32_e32 v141, 0x10000, v141
	v_xor_b32_e32 v143, 0x10000, v143
	v_xor_b32_e32 v152, 0x10000, v152
	v_mfma_f32_16x16x32_bf16 v[96:99], v[144:147], v[212:215], v[96:99]
	ds_read_b128 v[128:131], v139
	ds_read_b128 v[132:135], v139 offset:2048
	s_add_u32 m0, s46, 0x10000
	v_mfma_f32_16x16x32_bf16 v[100:103], v[144:147], v[216:219], v[100:103]
	global_load_lds_dwordx4 v248, s[42:43]
	v_mfma_f32_16x16x32_bf16 v[104:107], v[144:147], v[240:243], v[104:107]
	ds_read_b128 v[156:159], v143 offset:32768
	ds_read_b128 v[160:163], v143 offset:34816
	s_add_u32 m0, s46, 0x18000
	v_mfma_f32_16x16x32_bf16 v[108:111], v[144:147], v[244:247], v[108:111]
	global_load_lds_dwordx4 v222, s[44:45]
	v_mfma_f32_16x16x32_bf16 v[112:115], v[148:151], v[212:215], v[112:115]
	ds_read_b128 v[144:147], v139 offset:4096
	s_add_u32 m0, s46, 0x12000
	v_mfma_f32_16x16x32_bf16 v[116:119], v[148:151], v[216:219], v[116:119]
	global_load_lds_dwordx4 v249, s[42:43]
	ds_read_b128 v[164:167], v143 offset:36864
	ds_read_b128 v[202:205], v143 offset:38912
	v_mfma_f32_16x16x32_bf16 v[120:123], v[148:151], v[240:243], v[120:123]
	s_add_u32 m0, s46, 0x1a000
	v_mfma_f32_16x16x32_bf16 v[124:127], v[148:151], v[244:247], v[124:127]
	global_load_lds_dwordx4 v234, s[44:45]
	s_waitcnt lgkmcnt(4)
	v_mfma_f32_16x16x32_bf16 v[0:3], v[128:131], v[156:159], v[0:3]
	ds_read_b128 v[148:151], v139 offset:6144
	s_waitcnt lgkmcnt(4)
	v_mfma_f32_16x16x32_bf16 v[4:7], v[128:131], v[160:163], v[4:7]
	ds_read_b128 v[212:215], v152 offset:32768
	s_waitcnt lgkmcnt(3)
	v_mfma_f32_16x16x32_bf16 v[8:11], v[128:131], v[164:167], v[8:11]
	s_waitcnt lgkmcnt(2)
	v_mfma_f32_16x16x32_bf16 v[12:15], v[128:131], v[202:205], v[12:15]
	v_mfma_f32_16x16x32_bf16 v[16:19], v[132:135], v[156:159], v[16:19]
	ds_read_b128 v[128:131], v139 offset:8192
	v_mfma_f32_16x16x32_bf16 v[20:23], v[132:135], v[160:163], v[20:23]
	ds_read_b128 v[216:219], v152 offset:34816
	v_mfma_f32_16x16x32_bf16 v[24:27], v[132:135], v[164:167], v[24:27]
	v_mfma_f32_16x16x32_bf16 v[28:31], v[132:135], v[202:205], v[28:31]
	v_mfma_f32_16x16x32_bf16 v[32:35], v[144:147], v[156:159], v[32:35]
	ds_read_b128 v[132:135], v139 offset:10240
	v_mfma_f32_16x16x32_bf16 v[36:39], v[144:147], v[160:163], v[36:39]
	ds_read_b128 v[240:243], v152 offset:36864
	v_mfma_f32_16x16x32_bf16 v[40:43], v[144:147], v[164:167], v[40:43]
	s_add_u32 m0, s46, 0x14000
	v_mfma_f32_16x16x32_bf16 v[44:47], v[144:147], v[202:205], v[44:47]
	global_load_lds_dwordx4 v220, s[42:43]
	s_waitcnt lgkmcnt(5)
	v_mfma_f32_16x16x32_bf16 v[48:51], v[148:151], v[156:159], v[48:51]
	ds_read_b128 v[144:147], v139 offset:12288
	v_mfma_f32_16x16x32_bf16 v[52:55], v[148:151], v[160:163], v[52:55]
	ds_read_b128 v[244:247], v152 offset:38912
	v_mfma_f32_16x16x32_bf16 v[56:59], v[148:151], v[164:167], v[56:59]
	s_add_u32 m0, s46, 0x1c000
	v_mfma_f32_16x16x32_bf16 v[60:63], v[148:151], v[202:205], v[60:63]
	global_load_lds_dwordx4 v239, s[44:45]
	s_waitcnt lgkmcnt(5)
	v_mfma_f32_16x16x32_bf16 v[64:67], v[128:131], v[156:159], v[64:67]
	ds_read_b128 v[148:151], v139 offset:14336
	v_mfma_f32_16x16x32_bf16 v[68:71], v[128:131], v[160:163], v[68:71]
	v_mfma_f32_16x16x32_bf16 v[72:75], v[128:131], v[164:167], v[72:75]
	s_add_u32 m0, s46, 0x16000
	v_mfma_f32_16x16x32_bf16 v[76:79], v[128:131], v[202:205], v[76:79]
	global_load_lds_dwordx4 v221, s[42:43]
	s_waitcnt lgkmcnt(4)
	v_mfma_f32_16x16x32_bf16 v[80:83], v[132:135], v[156:159], v[80:83]
	ds_read_b128 v[128:131], v141
	v_mfma_f32_16x16x32_bf16 v[84:87], v[132:135], v[160:163], v[84:87]
	v_mfma_f32_16x16x32_bf16 v[88:91], v[132:135], v[164:167], v[88:91]
	s_add_u32 m0, s46, 0x1e000
	v_mfma_f32_16x16x32_bf16 v[92:95], v[132:135], v[202:205], v[92:95]
	global_load_lds_dwordx4 v252, s[44:45]
	s_add_u32 s42, s42, 0x80
	s_addc_u32 s43, s43, 0
	s_add_u32 s44, s44, 0x80
	s_addc_u32 s45, s45, 0
	s_waitcnt lgkmcnt(3)
	v_mfma_f32_16x16x32_bf16 v[96:99], v[144:147], v[156:159], v[96:99]
	ds_read_b128 v[132:135], v141 offset:2048
	v_mfma_f32_16x16x32_bf16 v[100:103], v[144:147], v[160:163], v[100:103]
	v_mfma_f32_16x16x32_bf16 v[104:107], v[144:147], v[164:167], v[104:107]
	v_mfma_f32_16x16x32_bf16 v[108:111], v[144:147], v[202:205], v[108:111]
	s_waitcnt lgkmcnt(2)
	v_mfma_f32_16x16x32_bf16 v[112:115], v[148:151], v[156:159], v[112:115]
	ds_read_b128 v[144:147], v141 offset:4096
	v_mfma_f32_16x16x32_bf16 v[116:119], v[148:151], v[160:163], v[116:119]
	v_mfma_f32_16x16x32_bf16 v[120:123], v[148:151], v[164:167], v[120:123]
	v_mfma_f32_16x16x32_bf16 v[124:127], v[148:151], v[202:205], v[124:127]
	s_waitcnt lgkmcnt(2)
	v_mfma_f32_16x16x32_bf16 v[0:3], v[128:131], v[212:215], v[0:3]
	ds_read_b128 v[148:151], v141 offset:6144
	v_mfma_f32_16x16x32_bf16 v[4:7], v[128:131], v[216:219], v[4:7]
	v_mfma_f32_16x16x32_bf16 v[8:11], v[128:131], v[240:243], v[8:11]
	v_mfma_f32_16x16x32_bf16 v[12:15], v[128:131], v[244:247], v[12:15]
	s_waitcnt lgkmcnt(2)
	v_mfma_f32_16x16x32_bf16 v[16:19], v[132:135], v[212:215], v[16:19]
	ds_read_b128 v[128:131], v141 offset:8192
	v_mfma_f32_16x16x32_bf16 v[20:23], v[132:135], v[216:219], v[20:23]
	v_mfma_f32_16x16x32_bf16 v[24:27], v[132:135], v[240:243], v[24:27]
	v_mfma_f32_16x16x32_bf16 v[28:31], v[132:135], v[244:247], v[28:31]
	s_waitcnt lgkmcnt(2)
	v_mfma_f32_16x16x32_bf16 v[32:35], v[144:147], v[212:215], v[32:35]
	ds_read_b128 v[132:135], v141 offset:10240
	v_mfma_f32_16x16x32_bf16 v[36:39], v[144:147], v[216:219], v[36:39]
	v_mfma_f32_16x16x32_bf16 v[40:43], v[144:147], v[240:243], v[40:43]
	v_mfma_f32_16x16x32_bf16 v[44:47], v[144:147], v[244:247], v[44:47]
	s_waitcnt lgkmcnt(2)
	v_mfma_f32_16x16x32_bf16 v[48:51], v[148:151], v[212:215], v[48:51]
	ds_read_b128 v[144:147], v141 offset:12288
	v_mfma_f32_16x16x32_bf16 v[52:55], v[148:151], v[216:219], v[52:55]
	v_mfma_f32_16x16x32_bf16 v[56:59], v[148:151], v[240:243], v[56:59]
	v_mfma_f32_16x16x32_bf16 v[60:63], v[148:151], v[244:247], v[60:63]
	s_waitcnt lgkmcnt(2)
	v_mfma_f32_16x16x32_bf16 v[64:67], v[128:131], v[212:215], v[64:67]
	ds_read_b128 v[148:151], v141 offset:14336
	v_mfma_f32_16x16x32_bf16 v[68:71], v[128:131], v[216:219], v[68:71]
	v_mfma_f32_16x16x32_bf16 v[72:75], v[128:131], v[240:243], v[72:75]
	v_mfma_f32_16x16x32_bf16 v[76:79], v[128:131], v[244:247], v[76:79]
	s_waitcnt lgkmcnt(2)
	v_mfma_f32_16x16x32_bf16 v[80:83], v[132:135], v[212:215], v[80:83]
	v_mfma_f32_16x16x32_bf16 v[84:87], v[132:135], v[216:219], v[84:87]
	v_mfma_f32_16x16x32_bf16 v[88:91], v[132:135], v[240:243], v[88:91]
	v_mfma_f32_16x16x32_bf16 v[92:95], v[132:135], v[244:247], v[92:95]
	s_waitcnt lgkmcnt(0)
	s_waitcnt vmcnt(0)
	s_barrier
	v_xor_b32_e32 v139, 0x10000, v139
	v_xor_b32_e32 v141, 0x10000, v141
	v_xor_b32_e32 v143, 0x10000, v143
	v_xor_b32_e32 v152, 0x10000, v152
	v_mfma_f32_16x16x32_bf16 v[96:99], v[144:147], v[212:215], v[96:99]
	ds_read_b128 v[128:131], v139
	ds_read_b128 v[132:135], v139 offset:2048
	s_mov_b32 m0, s46
	v_mfma_f32_16x16x32_bf16 v[100:103], v[144:147], v[216:219], v[100:103]
	global_load_lds_dwordx4 v248, s[42:43]
	v_mfma_f32_16x16x32_bf16 v[104:107], v[144:147], v[240:243], v[104:107]
	ds_read_b128 v[156:159], v143 offset:32768
	ds_read_b128 v[160:163], v143 offset:34816
	s_add_u32 m0, s46, 0x8000
	v_mfma_f32_16x16x32_bf16 v[108:111], v[144:147], v[244:247], v[108:111]
	global_load_lds_dwordx4 v222, s[44:45]
	v_mfma_f32_16x16x32_bf16 v[112:115], v[148:151], v[212:215], v[112:115]
	ds_read_b128 v[144:147], v139 offset:4096
	s_add_u32 m0, s46, 0x2000
	v_mfma_f32_16x16x32_bf16 v[116:119], v[148:151], v[216:219], v[116:119]
	global_load_lds_dwordx4 v249, s[42:43]
	ds_read_b128 v[164:167], v143 offset:36864
	ds_read_b128 v[202:205], v143 offset:38912
	v_mfma_f32_16x16x32_bf16 v[120:123], v[148:151], v[240:243], v[120:123]
	s_add_u32 m0, s46, 0xa000
	v_mfma_f32_16x16x32_bf16 v[124:127], v[148:151], v[244:247], v[124:127]
	global_load_lds_dwordx4 v234, s[44:45]
	s_waitcnt lgkmcnt(4)
	v_mfma_f32_16x16x32_bf16 v[0:3], v[128:131], v[156:159], v[0:3]
	ds_read_b128 v[148:151], v139 offset:6144
	s_waitcnt lgkmcnt(4)
	v_mfma_f32_16x16x32_bf16 v[4:7], v[128:131], v[160:163], v[4:7]
	ds_read_b128 v[212:215], v152 offset:32768
	s_waitcnt lgkmcnt(3)
	v_mfma_f32_16x16x32_bf16 v[8:11], v[128:131], v[164:167], v[8:11]
	s_waitcnt lgkmcnt(2)
	v_mfma_f32_16x16x32_bf16 v[12:15], v[128:131], v[202:205], v[12:15]
	v_mfma_f32_16x16x32_bf16 v[16:19], v[132:135], v[156:159], v[16:19]
	ds_read_b128 v[128:131], v139 offset:8192
	v_mfma_f32_16x16x32_bf16 v[20:23], v[132:135], v[160:163], v[20:23]
	ds_read_b128 v[216:219], v152 offset:34816
	v_mfma_f32_16x16x32_bf16 v[24:27], v[132:135], v[164:167], v[24:27]
	v_mfma_f32_16x16x32_bf16 v[28:31], v[132:135], v[202:205], v[28:31]
	v_mfma_f32_16x16x32_bf16 v[32:35], v[144:147], v[156:159], v[32:35]
	ds_read_b128 v[132:135], v139 offset:10240
	v_mfma_f32_16x16x32_bf16 v[36:39], v[144:147], v[160:163], v[36:39]
	ds_read_b128 v[240:243], v152 offset:36864
	v_mfma_f32_16x16x32_bf16 v[40:43], v[144:147], v[164:167], v[40:43]
	s_add_u32 m0, s46, 0x4000
	v_mfma_f32_16x16x32_bf16 v[44:47], v[144:147], v[202:205], v[44:47]
	global_load_lds_dwordx4 v220, s[42:43]
	s_waitcnt lgkmcnt(5)
	v_mfma_f32_16x16x32_bf16 v[48:51], v[148:151], v[156:159], v[48:51]
	ds_read_b128 v[144:147], v139 offset:12288
	v_mfma_f32_16x16x32_bf16 v[52:55], v[148:151], v[160:163], v[52:55]
	ds_read_b128 v[244:247], v152 offset:38912
	v_mfma_f32_16x16x32_bf16 v[56:59], v[148:151], v[164:167], v[56:59]
	s_add_u32 m0, s46, 0xc000
	v_mfma_f32_16x16x32_bf16 v[60:63], v[148:151], v[202:205], v[60:63]
	global_load_lds_dwordx4 v239, s[44:45]
	s_waitcnt lgkmcnt(5)
	v_mfma_f32_16x16x32_bf16 v[64:67], v[128:131], v[156:159], v[64:67]
	ds_read_b128 v[148:151], v139 offset:14336
	v_mfma_f32_16x16x32_bf16 v[68:71], v[128:131], v[160:163], v[68:71]
	v_mfma_f32_16x16x32_bf16 v[72:75], v[128:131], v[164:167], v[72:75]
	s_add_u32 m0, s46, 0x6000
	v_mfma_f32_16x16x32_bf16 v[76:79], v[128:131], v[202:205], v[76:79]
	global_load_lds_dwordx4 v221, s[42:43]
	s_waitcnt lgkmcnt(4)
	v_mfma_f32_16x16x32_bf16 v[80:83], v[132:135], v[156:159], v[80:83]
	ds_read_b128 v[128:131], v141
	v_mfma_f32_16x16x32_bf16 v[84:87], v[132:135], v[160:163], v[84:87]
	v_mfma_f32_16x16x32_bf16 v[88:91], v[132:135], v[164:167], v[88:91]
	s_add_u32 m0, s46, 0xe000
	v_mfma_f32_16x16x32_bf16 v[92:95], v[132:135], v[202:205], v[92:95]
	global_load_lds_dwordx4 v252, s[44:45]
	s_add_u32 s42, s42, 0x80
	s_addc_u32 s43, s43, 0
	s_add_u32 s44, s44, 0x80
	s_addc_u32 s45, s45, 0
	s_waitcnt lgkmcnt(3)
	v_mfma_f32_16x16x32_bf16 v[96:99], v[144:147], v[156:159], v[96:99]
	ds_read_b128 v[132:135], v141 offset:2048
	v_mfma_f32_16x16x32_bf16 v[100:103], v[144:147], v[160:163], v[100:103]
	v_mfma_f32_16x16x32_bf16 v[104:107], v[144:147], v[164:167], v[104:107]
	v_mfma_f32_16x16x32_bf16 v[108:111], v[144:147], v[202:205], v[108:111]
	s_waitcnt lgkmcnt(2)
	v_mfma_f32_16x16x32_bf16 v[112:115], v[148:151], v[156:159], v[112:115]
	ds_read_b128 v[144:147], v141 offset:4096
	v_mfma_f32_16x16x32_bf16 v[116:119], v[148:151], v[160:163], v[116:119]
	v_mfma_f32_16x16x32_bf16 v[120:123], v[148:151], v[164:167], v[120:123]
	v_mfma_f32_16x16x32_bf16 v[124:127], v[148:151], v[202:205], v[124:127]
	s_waitcnt lgkmcnt(2)
	v_mfma_f32_16x16x32_bf16 v[0:3], v[128:131], v[212:215], v[0:3]
	ds_read_b128 v[148:151], v141 offset:6144
	v_mfma_f32_16x16x32_bf16 v[4:7], v[128:131], v[216:219], v[4:7]
	v_mfma_f32_16x16x32_bf16 v[8:11], v[128:131], v[240:243], v[8:11]
	v_mfma_f32_16x16x32_bf16 v[12:15], v[128:131], v[244:247], v[12:15]
	s_waitcnt lgkmcnt(2)
	v_mfma_f32_16x16x32_bf16 v[16:19], v[132:135], v[212:215], v[16:19]
	ds_read_b128 v[128:131], v141 offset:8192
	v_mfma_f32_16x16x32_bf16 v[20:23], v[132:135], v[216:219], v[20:23]
	v_mfma_f32_16x16x32_bf16 v[24:27], v[132:135], v[240:243], v[24:27]
	v_mfma_f32_16x16x32_bf16 v[28:31], v[132:135], v[244:247], v[28:31]
	s_waitcnt lgkmcnt(2)
	v_mfma_f32_16x16x32_bf16 v[32:35], v[144:147], v[212:215], v[32:35]
	ds_read_b128 v[132:135], v141 offset:10240
	v_mfma_f32_16x16x32_bf16 v[36:39], v[144:147], v[216:219], v[36:39]
	v_mfma_f32_16x16x32_bf16 v[40:43], v[144:147], v[240:243], v[40:43]
	v_mfma_f32_16x16x32_bf16 v[44:47], v[144:147], v[244:247], v[44:47]
	s_waitcnt lgkmcnt(2)
	v_mfma_f32_16x16x32_bf16 v[48:51], v[148:151], v[212:215], v[48:51]
	ds_read_b128 v[144:147], v141 offset:12288
	v_mfma_f32_16x16x32_bf16 v[52:55], v[148:151], v[216:219], v[52:55]
	v_mfma_f32_16x16x32_bf16 v[56:59], v[148:151], v[240:243], v[56:59]
	v_mfma_f32_16x16x32_bf16 v[60:63], v[148:151], v[244:247], v[60:63]
	s_waitcnt lgkmcnt(2)
	v_mfma_f32_16x16x32_bf16 v[64:67], v[128:131], v[212:215], v[64:67]
	ds_read_b128 v[148:151], v141 offset:14336
	v_mfma_f32_16x16x32_bf16 v[68:71], v[128:131], v[216:219], v[68:71]
	v_mfma_f32_16x16x32_bf16 v[72:75], v[128:131], v[240:243], v[72:75]
	v_mfma_f32_16x16x32_bf16 v[76:79], v[128:131], v[244:247], v[76:79]
	s_waitcnt lgkmcnt(2)
	v_mfma_f32_16x16x32_bf16 v[80:83], v[132:135], v[212:215], v[80:83]
	v_mfma_f32_16x16x32_bf16 v[84:87], v[132:135], v[216:219], v[84:87]
	v_mfma_f32_16x16x32_bf16 v[88:91], v[132:135], v[240:243], v[88:91]
	v_mfma_f32_16x16x32_bf16 v[92:95], v[132:135], v[244:247], v[92:95]
	s_waitcnt lgkmcnt(0)
	s_waitcnt vmcnt(0)
	s_barrier
	v_xor_b32_e32 v139, 0x10000, v139
	v_xor_b32_e32 v141, 0x10000, v141
	v_xor_b32_e32 v143, 0x10000, v143
	v_xor_b32_e32 v152, 0x10000, v152
	v_mfma_f32_16x16x32_bf16 v[96:99], v[144:147], v[212:215], v[96:99]
	ds_read_b128 v[128:131], v139
	ds_read_b128 v[132:135], v139 offset:2048
	s_add_u32 m0, s46, 0x10000
	v_mfma_f32_16x16x32_bf16 v[100:103], v[144:147], v[216:219], v[100:103]
	global_load_lds_dwordx4 v248, s[42:43]
	v_mfma_f32_16x16x32_bf16 v[104:107], v[144:147], v[240:243], v[104:107]
	ds_read_b128 v[156:159], v143 offset:32768
	ds_read_b128 v[160:163], v143 offset:34816
	s_add_u32 m0, s46, 0x18000
	v_mfma_f32_16x16x32_bf16 v[108:111], v[144:147], v[244:247], v[108:111]
	global_load_lds_dwordx4 v222, s[44:45]
	v_mfma_f32_16x16x32_bf16 v[112:115], v[148:151], v[212:215], v[112:115]
	ds_read_b128 v[144:147], v139 offset:4096
	s_add_u32 m0, s46, 0x12000
	v_mfma_f32_16x16x32_bf16 v[116:119], v[148:151], v[216:219], v[116:119]
	global_load_lds_dwordx4 v249, s[42:43]
	ds_read_b128 v[164:167], v143 offset:36864
	ds_read_b128 v[202:205], v143 offset:38912
	v_mfma_f32_16x16x32_bf16 v[120:123], v[148:151], v[240:243], v[120:123]
	s_add_u32 m0, s46, 0x1a000
	v_mfma_f32_16x16x32_bf16 v[124:127], v[148:151], v[244:247], v[124:127]
	global_load_lds_dwordx4 v234, s[44:45]
	s_waitcnt lgkmcnt(4)
	v_mfma_f32_16x16x32_bf16 v[0:3], v[128:131], v[156:159], v[0:3]
	ds_read_b128 v[148:151], v139 offset:6144
	s_waitcnt lgkmcnt(4)
	v_mfma_f32_16x16x32_bf16 v[4:7], v[128:131], v[160:163], v[4:7]
	ds_read_b128 v[212:215], v152 offset:32768
	s_waitcnt lgkmcnt(3)
	v_mfma_f32_16x16x32_bf16 v[8:11], v[128:131], v[164:167], v[8:11]
	s_waitcnt lgkmcnt(2)
	v_mfma_f32_16x16x32_bf16 v[12:15], v[128:131], v[202:205], v[12:15]
	v_mfma_f32_16x16x32_bf16 v[16:19], v[132:135], v[156:159], v[16:19]
	ds_read_b128 v[128:131], v139 offset:8192
	v_mfma_f32_16x16x32_bf16 v[20:23], v[132:135], v[160:163], v[20:23]
	ds_read_b128 v[216:219], v152 offset:34816
	v_mfma_f32_16x16x32_bf16 v[24:27], v[132:135], v[164:167], v[24:27]
	v_mfma_f32_16x16x32_bf16 v[28:31], v[132:135], v[202:205], v[28:31]
	v_mfma_f32_16x16x32_bf16 v[32:35], v[144:147], v[156:159], v[32:35]
	ds_read_b128 v[132:135], v139 offset:10240
	v_mfma_f32_16x16x32_bf16 v[36:39], v[144:147], v[160:163], v[36:39]
	ds_read_b128 v[240:243], v152 offset:36864
	v_mfma_f32_16x16x32_bf16 v[40:43], v[144:147], v[164:167], v[40:43]
	s_add_u32 m0, s46, 0x14000
	v_mfma_f32_16x16x32_bf16 v[44:47], v[144:147], v[202:205], v[44:47]
	global_load_lds_dwordx4 v220, s[42:43]
	s_waitcnt lgkmcnt(5)
	v_mfma_f32_16x16x32_bf16 v[48:51], v[148:151], v[156:159], v[48:51]
	ds_read_b128 v[144:147], v139 offset:12288
	v_mfma_f32_16x16x32_bf16 v[52:55], v[148:151], v[160:163], v[52:55]
	ds_read_b128 v[244:247], v152 offset:38912
	v_mfma_f32_16x16x32_bf16 v[56:59], v[148:151], v[164:167], v[56:59]
	s_add_u32 m0, s46, 0x1c000
	v_mfma_f32_16x16x32_bf16 v[60:63], v[148:151], v[202:205], v[60:63]
	global_load_lds_dwordx4 v239, s[44:45]
	s_waitcnt lgkmcnt(5)
	v_mfma_f32_16x16x32_bf16 v[64:67], v[128:131], v[156:159], v[64:67]
	ds_read_b128 v[148:151], v139 offset:14336
	v_mfma_f32_16x16x32_bf16 v[68:71], v[128:131], v[160:163], v[68:71]
	v_mfma_f32_16x16x32_bf16 v[72:75], v[128:131], v[164:167], v[72:75]
	s_add_u32 m0, s46, 0x16000
	v_mfma_f32_16x16x32_bf16 v[76:79], v[128:131], v[202:205], v[76:79]
	global_load_lds_dwordx4 v221, s[42:43]
	s_waitcnt lgkmcnt(4)
	v_mfma_f32_16x16x32_bf16 v[80:83], v[132:135], v[156:159], v[80:83]
	ds_read_b128 v[128:131], v141
	v_mfma_f32_16x16x32_bf16 v[84:87], v[132:135], v[160:163], v[84:87]
	v_mfma_f32_16x16x32_bf16 v[88:91], v[132:135], v[164:167], v[88:91]
	s_add_u32 m0, s46, 0x1e000
	v_mfma_f32_16x16x32_bf16 v[92:95], v[132:135], v[202:205], v[92:95]
	global_load_lds_dwordx4 v252, s[44:45]
	s_add_u32 s42, s42, 0x80
	s_addc_u32 s43, s43, 0
	s_add_u32 s44, s44, 0x80
	s_addc_u32 s45, s45, 0
	s_waitcnt lgkmcnt(3)
	v_mfma_f32_16x16x32_bf16 v[96:99], v[144:147], v[156:159], v[96:99]
	ds_read_b128 v[132:135], v141 offset:2048
	v_mfma_f32_16x16x32_bf16 v[100:103], v[144:147], v[160:163], v[100:103]
	v_mfma_f32_16x16x32_bf16 v[104:107], v[144:147], v[164:167], v[104:107]
	v_mfma_f32_16x16x32_bf16 v[108:111], v[144:147], v[202:205], v[108:111]
	s_waitcnt lgkmcnt(2)
	v_mfma_f32_16x16x32_bf16 v[112:115], v[148:151], v[156:159], v[112:115]
	ds_read_b128 v[144:147], v141 offset:4096
	v_mfma_f32_16x16x32_bf16 v[116:119], v[148:151], v[160:163], v[116:119]
	v_mfma_f32_16x16x32_bf16 v[120:123], v[148:151], v[164:167], v[120:123]
	v_mfma_f32_16x16x32_bf16 v[124:127], v[148:151], v[202:205], v[124:127]
	s_waitcnt lgkmcnt(2)
	v_mfma_f32_16x16x32_bf16 v[0:3], v[128:131], v[212:215], v[0:3]
	ds_read_b128 v[148:151], v141 offset:6144
	v_mfma_f32_16x16x32_bf16 v[4:7], v[128:131], v[216:219], v[4:7]
	v_mfma_f32_16x16x32_bf16 v[8:11], v[128:131], v[240:243], v[8:11]
	v_mfma_f32_16x16x32_bf16 v[12:15], v[128:131], v[244:247], v[12:15]
	s_waitcnt lgkmcnt(2)
	v_mfma_f32_16x16x32_bf16 v[16:19], v[132:135], v[212:215], v[16:19]
	ds_read_b128 v[128:131], v141 offset:8192
	v_mfma_f32_16x16x32_bf16 v[20:23], v[132:135], v[216:219], v[20:23]
	v_mfma_f32_16x16x32_bf16 v[24:27], v[132:135], v[240:243], v[24:27]
	v_mfma_f32_16x16x32_bf16 v[28:31], v[132:135], v[244:247], v[28:31]
	s_waitcnt lgkmcnt(2)
	v_mfma_f32_16x16x32_bf16 v[32:35], v[144:147], v[212:215], v[32:35]
	ds_read_b128 v[132:135], v141 offset:10240
	v_mfma_f32_16x16x32_bf16 v[36:39], v[144:147], v[216:219], v[36:39]
	v_mfma_f32_16x16x32_bf16 v[40:43], v[144:147], v[240:243], v[40:43]
	v_mfma_f32_16x16x32_bf16 v[44:47], v[144:147], v[244:247], v[44:47]
	s_waitcnt lgkmcnt(2)
	v_mfma_f32_16x16x32_bf16 v[48:51], v[148:151], v[212:215], v[48:51]
	ds_read_b128 v[144:147], v141 offset:12288
	v_mfma_f32_16x16x32_bf16 v[52:55], v[148:151], v[216:219], v[52:55]
	v_mfma_f32_16x16x32_bf16 v[56:59], v[148:151], v[240:243], v[56:59]
	v_mfma_f32_16x16x32_bf16 v[60:63], v[148:151], v[244:247], v[60:63]
	s_waitcnt lgkmcnt(2)
	v_mfma_f32_16x16x32_bf16 v[64:67], v[128:131], v[212:215], v[64:67]
	ds_read_b128 v[148:151], v141 offset:14336
	v_mfma_f32_16x16x32_bf16 v[68:71], v[128:131], v[216:219], v[68:71]
	v_mfma_f32_16x16x32_bf16 v[72:75], v[128:131], v[240:243], v[72:75]
	v_mfma_f32_16x16x32_bf16 v[76:79], v[128:131], v[244:247], v[76:79]
	s_waitcnt lgkmcnt(2)
	v_mfma_f32_16x16x32_bf16 v[80:83], v[132:135], v[212:215], v[80:83]
	v_mfma_f32_16x16x32_bf16 v[84:87], v[132:135], v[216:219], v[84:87]
	v_mfma_f32_16x16x32_bf16 v[88:91], v[132:135], v[240:243], v[88:91]
	v_mfma_f32_16x16x32_bf16 v[92:95], v[132:135], v[244:247], v[92:95]
	s_waitcnt lgkmcnt(0)
	s_waitcnt vmcnt(0)
	s_barrier
	v_xor_b32_e32 v139, 0x10000, v139
	v_xor_b32_e32 v141, 0x10000, v141
	v_xor_b32_e32 v143, 0x10000, v143
	v_xor_b32_e32 v152, 0x10000, v152
	v_mfma_f32_16x16x32_bf16 v[96:99], v[144:147], v[212:215], v[96:99]
	ds_read_b128 v[128:131], v139
	ds_read_b128 v[132:135], v139 offset:2048
	s_mov_b32 m0, s46
	v_mfma_f32_16x16x32_bf16 v[100:103], v[144:147], v[216:219], v[100:103]
	global_load_lds_dwordx4 v248, s[42:43]
	v_mfma_f32_16x16x32_bf16 v[104:107], v[144:147], v[240:243], v[104:107]
	ds_read_b128 v[156:159], v143 offset:32768
	ds_read_b128 v[160:163], v143 offset:34816
	s_add_u32 m0, s46, 0x8000
	v_mfma_f32_16x16x32_bf16 v[108:111], v[144:147], v[244:247], v[108:111]
	global_load_lds_dwordx4 v222, s[44:45]
	v_mfma_f32_16x16x32_bf16 v[112:115], v[148:151], v[212:215], v[112:115]
	ds_read_b128 v[144:147], v139 offset:4096
	s_add_u32 m0, s46, 0x2000
	v_mfma_f32_16x16x32_bf16 v[116:119], v[148:151], v[216:219], v[116:119]
	global_load_lds_dwordx4 v249, s[42:43]
	ds_read_b128 v[164:167], v143 offset:36864
	ds_read_b128 v[202:205], v143 offset:38912
	v_mfma_f32_16x16x32_bf16 v[120:123], v[148:151], v[240:243], v[120:123]
	s_add_u32 m0, s46, 0xa000
	v_mfma_f32_16x16x32_bf16 v[124:127], v[148:151], v[244:247], v[124:127]
	global_load_lds_dwordx4 v234, s[44:45]
	s_waitcnt lgkmcnt(4)
	v_mfma_f32_16x16x32_bf16 v[0:3], v[128:131], v[156:159], v[0:3]
	ds_read_b128 v[148:151], v139 offset:6144
	s_waitcnt lgkmcnt(4)
	v_mfma_f32_16x16x32_bf16 v[4:7], v[128:131], v[160:163], v[4:7]
	ds_read_b128 v[212:215], v152 offset:32768
	s_waitcnt lgkmcnt(3)
	v_mfma_f32_16x16x32_bf16 v[8:11], v[128:131], v[164:167], v[8:11]
	s_waitcnt lgkmcnt(2)
	v_mfma_f32_16x16x32_bf16 v[12:15], v[128:131], v[202:205], v[12:15]
	v_mfma_f32_16x16x32_bf16 v[16:19], v[132:135], v[156:159], v[16:19]
	ds_read_b128 v[128:131], v139 offset:8192
	v_mfma_f32_16x16x32_bf16 v[20:23], v[132:135], v[160:163], v[20:23]
	ds_read_b128 v[216:219], v152 offset:34816
	v_mfma_f32_16x16x32_bf16 v[24:27], v[132:135], v[164:167], v[24:27]
	v_mfma_f32_16x16x32_bf16 v[28:31], v[132:135], v[202:205], v[28:31]
	v_mfma_f32_16x16x32_bf16 v[32:35], v[144:147], v[156:159], v[32:35]
	ds_read_b128 v[132:135], v139 offset:10240
	v_mfma_f32_16x16x32_bf16 v[36:39], v[144:147], v[160:163], v[36:39]
	ds_read_b128 v[240:243], v152 offset:36864
	v_mfma_f32_16x16x32_bf16 v[40:43], v[144:147], v[164:167], v[40:43]
	s_add_u32 m0, s46, 0x4000
	v_mfma_f32_16x16x32_bf16 v[44:47], v[144:147], v[202:205], v[44:47]
	global_load_lds_dwordx4 v220, s[42:43]
	s_waitcnt lgkmcnt(5)
	v_mfma_f32_16x16x32_bf16 v[48:51], v[148:151], v[156:159], v[48:51]
	ds_read_b128 v[144:147], v139 offset:12288
	v_mfma_f32_16x16x32_bf16 v[52:55], v[148:151], v[160:163], v[52:55]
	ds_read_b128 v[244:247], v152 offset:38912
	v_mfma_f32_16x16x32_bf16 v[56:59], v[148:151], v[164:167], v[56:59]
	s_add_u32 m0, s46, 0xc000
	v_mfma_f32_16x16x32_bf16 v[60:63], v[148:151], v[202:205], v[60:63]
	global_load_lds_dwordx4 v239, s[44:45]
	s_waitcnt lgkmcnt(5)
	v_mfma_f32_16x16x32_bf16 v[64:67], v[128:131], v[156:159], v[64:67]
	ds_read_b128 v[148:151], v139 offset:14336
	v_mfma_f32_16x16x32_bf16 v[68:71], v[128:131], v[160:163], v[68:71]
	v_mfma_f32_16x16x32_bf16 v[72:75], v[128:131], v[164:167], v[72:75]
	s_add_u32 m0, s46, 0x6000
	v_mfma_f32_16x16x32_bf16 v[76:79], v[128:131], v[202:205], v[76:79]
	global_load_lds_dwordx4 v221, s[42:43]
	s_waitcnt lgkmcnt(4)
	v_mfma_f32_16x16x32_bf16 v[80:83], v[132:135], v[156:159], v[80:83]
	ds_read_b128 v[128:131], v141
	v_mfma_f32_16x16x32_bf16 v[84:87], v[132:135], v[160:163], v[84:87]
	v_mfma_f32_16x16x32_bf16 v[88:91], v[132:135], v[164:167], v[88:91]
	s_add_u32 m0, s46, 0xe000
	v_mfma_f32_16x16x32_bf16 v[92:95], v[132:135], v[202:205], v[92:95]
	global_load_lds_dwordx4 v252, s[44:45]
	s_add_u32 s42, s42, 0x80
	s_addc_u32 s43, s43, 0
	s_add_u32 s44, s44, 0x80
	s_addc_u32 s45, s45, 0
	s_waitcnt lgkmcnt(3)
	v_mfma_f32_16x16x32_bf16 v[96:99], v[144:147], v[156:159], v[96:99]
	ds_read_b128 v[132:135], v141 offset:2048
	v_mfma_f32_16x16x32_bf16 v[100:103], v[144:147], v[160:163], v[100:103]
	v_mfma_f32_16x16x32_bf16 v[104:107], v[144:147], v[164:167], v[104:107]
	v_mfma_f32_16x16x32_bf16 v[108:111], v[144:147], v[202:205], v[108:111]
	s_waitcnt lgkmcnt(2)
	v_mfma_f32_16x16x32_bf16 v[112:115], v[148:151], v[156:159], v[112:115]
	ds_read_b128 v[144:147], v141 offset:4096
	v_mfma_f32_16x16x32_bf16 v[116:119], v[148:151], v[160:163], v[116:119]
	v_mfma_f32_16x16x32_bf16 v[120:123], v[148:151], v[164:167], v[120:123]
	v_mfma_f32_16x16x32_bf16 v[124:127], v[148:151], v[202:205], v[124:127]
	s_waitcnt lgkmcnt(2)
	v_mfma_f32_16x16x32_bf16 v[0:3], v[128:131], v[212:215], v[0:3]
	ds_read_b128 v[148:151], v141 offset:6144
	v_mfma_f32_16x16x32_bf16 v[4:7], v[128:131], v[216:219], v[4:7]
	v_mfma_f32_16x16x32_bf16 v[8:11], v[128:131], v[240:243], v[8:11]
	v_mfma_f32_16x16x32_bf16 v[12:15], v[128:131], v[244:247], v[12:15]
	s_waitcnt lgkmcnt(2)
	v_mfma_f32_16x16x32_bf16 v[16:19], v[132:135], v[212:215], v[16:19]
	ds_read_b128 v[128:131], v141 offset:8192
	v_mfma_f32_16x16x32_bf16 v[20:23], v[132:135], v[216:219], v[20:23]
	v_mfma_f32_16x16x32_bf16 v[24:27], v[132:135], v[240:243], v[24:27]
	v_mfma_f32_16x16x32_bf16 v[28:31], v[132:135], v[244:247], v[28:31]
	s_waitcnt lgkmcnt(2)
	v_mfma_f32_16x16x32_bf16 v[32:35], v[144:147], v[212:215], v[32:35]
	ds_read_b128 v[132:135], v141 offset:10240
	v_mfma_f32_16x16x32_bf16 v[36:39], v[144:147], v[216:219], v[36:39]
	v_mfma_f32_16x16x32_bf16 v[40:43], v[144:147], v[240:243], v[40:43]
	v_mfma_f32_16x16x32_bf16 v[44:47], v[144:147], v[244:247], v[44:47]
	s_waitcnt lgkmcnt(2)
	v_mfma_f32_16x16x32_bf16 v[48:51], v[148:151], v[212:215], v[48:51]
	ds_read_b128 v[144:147], v141 offset:12288
	v_mfma_f32_16x16x32_bf16 v[52:55], v[148:151], v[216:219], v[52:55]
	v_mfma_f32_16x16x32_bf16 v[56:59], v[148:151], v[240:243], v[56:59]
	v_mfma_f32_16x16x32_bf16 v[60:63], v[148:151], v[244:247], v[60:63]
	s_waitcnt lgkmcnt(2)
	v_mfma_f32_16x16x32_bf16 v[64:67], v[128:131], v[212:215], v[64:67]
	ds_read_b128 v[148:151], v141 offset:14336
	v_mfma_f32_16x16x32_bf16 v[68:71], v[128:131], v[216:219], v[68:71]
	v_mfma_f32_16x16x32_bf16 v[72:75], v[128:131], v[240:243], v[72:75]
	v_mfma_f32_16x16x32_bf16 v[76:79], v[128:131], v[244:247], v[76:79]
	s_waitcnt lgkmcnt(2)
	v_mfma_f32_16x16x32_bf16 v[80:83], v[132:135], v[212:215], v[80:83]
	v_mfma_f32_16x16x32_bf16 v[84:87], v[132:135], v[216:219], v[84:87]
	v_mfma_f32_16x16x32_bf16 v[88:91], v[132:135], v[240:243], v[88:91]
	v_mfma_f32_16x16x32_bf16 v[92:95], v[132:135], v[244:247], v[92:95]
	s_waitcnt lgkmcnt(0)
	s_waitcnt vmcnt(0)
	s_barrier
	v_xor_b32_e32 v139, 0x10000, v139
	v_xor_b32_e32 v141, 0x10000, v141
	v_xor_b32_e32 v143, 0x10000, v143
	v_xor_b32_e32 v152, 0x10000, v152
	v_mfma_f32_16x16x32_bf16 v[96:99], v[144:147], v[212:215], v[96:99]
	ds_read_b128 v[128:131], v139
	ds_read_b128 v[132:135], v139 offset:2048
	s_add_u32 m0, s46, 0x10000
	v_mfma_f32_16x16x32_bf16 v[100:103], v[144:147], v[216:219], v[100:103]
	global_load_lds_dwordx4 v248, s[42:43]
	v_mfma_f32_16x16x32_bf16 v[104:107], v[144:147], v[240:243], v[104:107]
	ds_read_b128 v[156:159], v143 offset:32768
	ds_read_b128 v[160:163], v143 offset:34816
	s_add_u32 m0, s46, 0x18000
	v_mfma_f32_16x16x32_bf16 v[108:111], v[144:147], v[244:247], v[108:111]
	global_load_lds_dwordx4 v222, s[44:45]
	v_mfma_f32_16x16x32_bf16 v[112:115], v[148:151], v[212:215], v[112:115]
	ds_read_b128 v[144:147], v139 offset:4096
	s_add_u32 m0, s46, 0x12000
	v_mfma_f32_16x16x32_bf16 v[116:119], v[148:151], v[216:219], v[116:119]
	global_load_lds_dwordx4 v249, s[42:43]
	ds_read_b128 v[164:167], v143 offset:36864
	ds_read_b128 v[202:205], v143 offset:38912
	v_mfma_f32_16x16x32_bf16 v[120:123], v[148:151], v[240:243], v[120:123]
	s_add_u32 m0, s46, 0x1a000
	v_mfma_f32_16x16x32_bf16 v[124:127], v[148:151], v[244:247], v[124:127]
	global_load_lds_dwordx4 v234, s[44:45]
	s_waitcnt lgkmcnt(4)
	v_mfma_f32_16x16x32_bf16 v[0:3], v[128:131], v[156:159], v[0:3]
	ds_read_b128 v[148:151], v139 offset:6144
	s_waitcnt lgkmcnt(4)
	v_mfma_f32_16x16x32_bf16 v[4:7], v[128:131], v[160:163], v[4:7]
	ds_read_b128 v[212:215], v152 offset:32768
	s_waitcnt lgkmcnt(3)
	v_mfma_f32_16x16x32_bf16 v[8:11], v[128:131], v[164:167], v[8:11]
	s_waitcnt lgkmcnt(2)
	v_mfma_f32_16x16x32_bf16 v[12:15], v[128:131], v[202:205], v[12:15]
	v_mfma_f32_16x16x32_bf16 v[16:19], v[132:135], v[156:159], v[16:19]
	ds_read_b128 v[128:131], v139 offset:8192
	v_mfma_f32_16x16x32_bf16 v[20:23], v[132:135], v[160:163], v[20:23]
	ds_read_b128 v[216:219], v152 offset:34816
	v_mfma_f32_16x16x32_bf16 v[24:27], v[132:135], v[164:167], v[24:27]
	v_mfma_f32_16x16x32_bf16 v[28:31], v[132:135], v[202:205], v[28:31]
	v_mfma_f32_16x16x32_bf16 v[32:35], v[144:147], v[156:159], v[32:35]
	ds_read_b128 v[132:135], v139 offset:10240
	v_mfma_f32_16x16x32_bf16 v[36:39], v[144:147], v[160:163], v[36:39]
	ds_read_b128 v[240:243], v152 offset:36864
	v_mfma_f32_16x16x32_bf16 v[40:43], v[144:147], v[164:167], v[40:43]
	s_add_u32 m0, s46, 0x14000
	v_mfma_f32_16x16x32_bf16 v[44:47], v[144:147], v[202:205], v[44:47]
	global_load_lds_dwordx4 v220, s[42:43]
	s_waitcnt lgkmcnt(5)
	v_mfma_f32_16x16x32_bf16 v[48:51], v[148:151], v[156:159], v[48:51]
	ds_read_b128 v[144:147], v139 offset:12288
	v_mfma_f32_16x16x32_bf16 v[52:55], v[148:151], v[160:163], v[52:55]
	ds_read_b128 v[244:247], v152 offset:38912
	v_mfma_f32_16x16x32_bf16 v[56:59], v[148:151], v[164:167], v[56:59]
	s_add_u32 m0, s46, 0x1c000
	v_mfma_f32_16x16x32_bf16 v[60:63], v[148:151], v[202:205], v[60:63]
	global_load_lds_dwordx4 v239, s[44:45]
	s_waitcnt lgkmcnt(5)
	v_mfma_f32_16x16x32_bf16 v[64:67], v[128:131], v[156:159], v[64:67]
	ds_read_b128 v[148:151], v139 offset:14336
	v_mfma_f32_16x16x32_bf16 v[68:71], v[128:131], v[160:163], v[68:71]
	v_mfma_f32_16x16x32_bf16 v[72:75], v[128:131], v[164:167], v[72:75]
	s_add_u32 m0, s46, 0x16000
	v_mfma_f32_16x16x32_bf16 v[76:79], v[128:131], v[202:205], v[76:79]
	global_load_lds_dwordx4 v221, s[42:43]
	s_waitcnt lgkmcnt(4)
	v_mfma_f32_16x16x32_bf16 v[80:83], v[132:135], v[156:159], v[80:83]
	ds_read_b128 v[128:131], v141
	v_mfma_f32_16x16x32_bf16 v[84:87], v[132:135], v[160:163], v[84:87]
	v_mfma_f32_16x16x32_bf16 v[88:91], v[132:135], v[164:167], v[88:91]
	s_add_u32 m0, s46, 0x1e000
	v_mfma_f32_16x16x32_bf16 v[92:95], v[132:135], v[202:205], v[92:95]
	global_load_lds_dwordx4 v252, s[44:45]
	s_add_u32 s42, s42, 0x80
	s_addc_u32 s43, s43, 0
	s_add_u32 s44, s44, 0x80
	s_addc_u32 s45, s45, 0
	s_waitcnt lgkmcnt(3)
	v_mfma_f32_16x16x32_bf16 v[96:99], v[144:147], v[156:159], v[96:99]
	ds_read_b128 v[132:135], v141 offset:2048
	v_mfma_f32_16x16x32_bf16 v[100:103], v[144:147], v[160:163], v[100:103]
	v_mfma_f32_16x16x32_bf16 v[104:107], v[144:147], v[164:167], v[104:107]
	v_mfma_f32_16x16x32_bf16 v[108:111], v[144:147], v[202:205], v[108:111]
	s_waitcnt lgkmcnt(2)
	v_mfma_f32_16x16x32_bf16 v[112:115], v[148:151], v[156:159], v[112:115]
	ds_read_b128 v[144:147], v141 offset:4096
	v_mfma_f32_16x16x32_bf16 v[116:119], v[148:151], v[160:163], v[116:119]
	v_mfma_f32_16x16x32_bf16 v[120:123], v[148:151], v[164:167], v[120:123]
	v_mfma_f32_16x16x32_bf16 v[124:127], v[148:151], v[202:205], v[124:127]
	s_waitcnt lgkmcnt(2)
	v_mfma_f32_16x16x32_bf16 v[0:3], v[128:131], v[212:215], v[0:3]
	ds_read_b128 v[148:151], v141 offset:6144
	v_mfma_f32_16x16x32_bf16 v[4:7], v[128:131], v[216:219], v[4:7]
	v_mfma_f32_16x16x32_bf16 v[8:11], v[128:131], v[240:243], v[8:11]
	v_mfma_f32_16x16x32_bf16 v[12:15], v[128:131], v[244:247], v[12:15]
	s_waitcnt lgkmcnt(2)
	v_mfma_f32_16x16x32_bf16 v[16:19], v[132:135], v[212:215], v[16:19]
	ds_read_b128 v[128:131], v141 offset:8192
	v_mfma_f32_16x16x32_bf16 v[20:23], v[132:135], v[216:219], v[20:23]
	v_mfma_f32_16x16x32_bf16 v[24:27], v[132:135], v[240:243], v[24:27]
	v_mfma_f32_16x16x32_bf16 v[28:31], v[132:135], v[244:247], v[28:31]
	s_waitcnt lgkmcnt(2)
	v_mfma_f32_16x16x32_bf16 v[32:35], v[144:147], v[212:215], v[32:35]
	ds_read_b128 v[132:135], v141 offset:10240
	v_mfma_f32_16x16x32_bf16 v[36:39], v[144:147], v[216:219], v[36:39]
	v_mfma_f32_16x16x32_bf16 v[40:43], v[144:147], v[240:243], v[40:43]
	v_mfma_f32_16x16x32_bf16 v[44:47], v[144:147], v[244:247], v[44:47]
	s_waitcnt lgkmcnt(2)
	v_mfma_f32_16x16x32_bf16 v[48:51], v[148:151], v[212:215], v[48:51]
	ds_read_b128 v[144:147], v141 offset:12288
	v_mfma_f32_16x16x32_bf16 v[52:55], v[148:151], v[216:219], v[52:55]
	v_mfma_f32_16x16x32_bf16 v[56:59], v[148:151], v[240:243], v[56:59]
	v_mfma_f32_16x16x32_bf16 v[60:63], v[148:151], v[244:247], v[60:63]
	s_waitcnt lgkmcnt(2)
	v_mfma_f32_16x16x32_bf16 v[64:67], v[128:131], v[212:215], v[64:67]
	ds_read_b128 v[148:151], v141 offset:14336
	v_mfma_f32_16x16x32_bf16 v[68:71], v[128:131], v[216:219], v[68:71]
	v_mfma_f32_16x16x32_bf16 v[72:75], v[128:131], v[240:243], v[72:75]
	v_mfma_f32_16x16x32_bf16 v[76:79], v[128:131], v[244:247], v[76:79]
	s_waitcnt lgkmcnt(2)
	v_mfma_f32_16x16x32_bf16 v[80:83], v[132:135], v[212:215], v[80:83]
	v_mfma_f32_16x16x32_bf16 v[84:87], v[132:135], v[216:219], v[84:87]
	v_mfma_f32_16x16x32_bf16 v[88:91], v[132:135], v[240:243], v[88:91]
	v_mfma_f32_16x16x32_bf16 v[92:95], v[132:135], v[244:247], v[92:95]
	s_waitcnt lgkmcnt(0)
	s_waitcnt vmcnt(0)
	s_barrier
	v_xor_b32_e32 v139, 0x10000, v139
	v_xor_b32_e32 v141, 0x10000, v141
	v_xor_b32_e32 v143, 0x10000, v143
	v_xor_b32_e32 v152, 0x10000, v152
	v_mfma_f32_16x16x32_bf16 v[96:99], v[144:147], v[212:215], v[96:99]
	ds_read_b128 v[128:131], v139
	ds_read_b128 v[132:135], v139 offset:2048
	s_mov_b32 m0, s46
	v_mfma_f32_16x16x32_bf16 v[100:103], v[144:147], v[216:219], v[100:103]
	global_load_lds_dwordx4 v248, s[42:43]
	v_mfma_f32_16x16x32_bf16 v[104:107], v[144:147], v[240:243], v[104:107]
	ds_read_b128 v[156:159], v143 offset:32768
	ds_read_b128 v[160:163], v143 offset:34816
	s_add_u32 m0, s46, 0x8000
	v_mfma_f32_16x16x32_bf16 v[108:111], v[144:147], v[244:247], v[108:111]
	global_load_lds_dwordx4 v222, s[44:45]
	v_mfma_f32_16x16x32_bf16 v[112:115], v[148:151], v[212:215], v[112:115]
	ds_read_b128 v[144:147], v139 offset:4096
	s_add_u32 m0, s46, 0x2000
	v_mfma_f32_16x16x32_bf16 v[116:119], v[148:151], v[216:219], v[116:119]
	global_load_lds_dwordx4 v249, s[42:43]
	ds_read_b128 v[164:167], v143 offset:36864
	ds_read_b128 v[202:205], v143 offset:38912
	v_mfma_f32_16x16x32_bf16 v[120:123], v[148:151], v[240:243], v[120:123]
	s_add_u32 m0, s46, 0xa000
	v_mfma_f32_16x16x32_bf16 v[124:127], v[148:151], v[244:247], v[124:127]
	global_load_lds_dwordx4 v234, s[44:45]
	s_waitcnt lgkmcnt(4)
	v_mfma_f32_16x16x32_bf16 v[0:3], v[128:131], v[156:159], v[0:3]
	ds_read_b128 v[148:151], v139 offset:6144
	s_waitcnt lgkmcnt(4)
	v_mfma_f32_16x16x32_bf16 v[4:7], v[128:131], v[160:163], v[4:7]
	ds_read_b128 v[212:215], v152 offset:32768
	s_waitcnt lgkmcnt(3)
	v_mfma_f32_16x16x32_bf16 v[8:11], v[128:131], v[164:167], v[8:11]
	s_waitcnt lgkmcnt(2)
	v_mfma_f32_16x16x32_bf16 v[12:15], v[128:131], v[202:205], v[12:15]
	v_mfma_f32_16x16x32_bf16 v[16:19], v[132:135], v[156:159], v[16:19]
	ds_read_b128 v[128:131], v139 offset:8192
	v_mfma_f32_16x16x32_bf16 v[20:23], v[132:135], v[160:163], v[20:23]
	ds_read_b128 v[216:219], v152 offset:34816
	v_mfma_f32_16x16x32_bf16 v[24:27], v[132:135], v[164:167], v[24:27]
	v_mfma_f32_16x16x32_bf16 v[28:31], v[132:135], v[202:205], v[28:31]
	v_mfma_f32_16x16x32_bf16 v[32:35], v[144:147], v[156:159], v[32:35]
	ds_read_b128 v[132:135], v139 offset:10240
	v_mfma_f32_16x16x32_bf16 v[36:39], v[144:147], v[160:163], v[36:39]
	ds_read_b128 v[240:243], v152 offset:36864
	v_mfma_f32_16x16x32_bf16 v[40:43], v[144:147], v[164:167], v[40:43]
	s_add_u32 m0, s46, 0x4000
	v_mfma_f32_16x16x32_bf16 v[44:47], v[144:147], v[202:205], v[44:47]
	global_load_lds_dwordx4 v220, s[42:43]
	s_waitcnt lgkmcnt(5)
	v_mfma_f32_16x16x32_bf16 v[48:51], v[148:151], v[156:159], v[48:51]
	ds_read_b128 v[144:147], v139 offset:12288
	v_mfma_f32_16x16x32_bf16 v[52:55], v[148:151], v[160:163], v[52:55]
	ds_read_b128 v[244:247], v152 offset:38912
	v_mfma_f32_16x16x32_bf16 v[56:59], v[148:151], v[164:167], v[56:59]
	s_add_u32 m0, s46, 0xc000
	v_mfma_f32_16x16x32_bf16 v[60:63], v[148:151], v[202:205], v[60:63]
	global_load_lds_dwordx4 v239, s[44:45]
	s_waitcnt lgkmcnt(5)
	v_mfma_f32_16x16x32_bf16 v[64:67], v[128:131], v[156:159], v[64:67]
	ds_read_b128 v[148:151], v139 offset:14336
	v_mfma_f32_16x16x32_bf16 v[68:71], v[128:131], v[160:163], v[68:71]
	v_mfma_f32_16x16x32_bf16 v[72:75], v[128:131], v[164:167], v[72:75]
	s_add_u32 m0, s46, 0x6000
	v_mfma_f32_16x16x32_bf16 v[76:79], v[128:131], v[202:205], v[76:79]
	global_load_lds_dwordx4 v221, s[42:43]
	s_waitcnt lgkmcnt(4)
	v_mfma_f32_16x16x32_bf16 v[80:83], v[132:135], v[156:159], v[80:83]
	ds_read_b128 v[128:131], v141
	v_mfma_f32_16x16x32_bf16 v[84:87], v[132:135], v[160:163], v[84:87]
	v_mfma_f32_16x16x32_bf16 v[88:91], v[132:135], v[164:167], v[88:91]
	s_add_u32 m0, s46, 0xe000
	v_mfma_f32_16x16x32_bf16 v[92:95], v[132:135], v[202:205], v[92:95]
	global_load_lds_dwordx4 v252, s[44:45]
	s_add_u32 s42, s42, 0x80
	s_addc_u32 s43, s43, 0
	s_add_u32 s44, s44, 0x80
	s_addc_u32 s45, s45, 0
	s_waitcnt lgkmcnt(3)
	v_mfma_f32_16x16x32_bf16 v[96:99], v[144:147], v[156:159], v[96:99]
	ds_read_b128 v[132:135], v141 offset:2048
	v_mfma_f32_16x16x32_bf16 v[100:103], v[144:147], v[160:163], v[100:103]
	v_mfma_f32_16x16x32_bf16 v[104:107], v[144:147], v[164:167], v[104:107]
	v_mfma_f32_16x16x32_bf16 v[108:111], v[144:147], v[202:205], v[108:111]
	s_waitcnt lgkmcnt(2)
	v_mfma_f32_16x16x32_bf16 v[112:115], v[148:151], v[156:159], v[112:115]
	ds_read_b128 v[144:147], v141 offset:4096
	v_mfma_f32_16x16x32_bf16 v[116:119], v[148:151], v[160:163], v[116:119]
	v_mfma_f32_16x16x32_bf16 v[120:123], v[148:151], v[164:167], v[120:123]
	v_mfma_f32_16x16x32_bf16 v[124:127], v[148:151], v[202:205], v[124:127]
	s_waitcnt lgkmcnt(2)
	v_mfma_f32_16x16x32_bf16 v[0:3], v[128:131], v[212:215], v[0:3]
	ds_read_b128 v[148:151], v141 offset:6144
	v_mfma_f32_16x16x32_bf16 v[4:7], v[128:131], v[216:219], v[4:7]
	v_mfma_f32_16x16x32_bf16 v[8:11], v[128:131], v[240:243], v[8:11]
	v_mfma_f32_16x16x32_bf16 v[12:15], v[128:131], v[244:247], v[12:15]
	s_waitcnt lgkmcnt(2)
	v_mfma_f32_16x16x32_bf16 v[16:19], v[132:135], v[212:215], v[16:19]
	ds_read_b128 v[128:131], v141 offset:8192
	v_mfma_f32_16x16x32_bf16 v[20:23], v[132:135], v[216:219], v[20:23]
	v_mfma_f32_16x16x32_bf16 v[24:27], v[132:135], v[240:243], v[24:27]
	v_mfma_f32_16x16x32_bf16 v[28:31], v[132:135], v[244:247], v[28:31]
	s_waitcnt lgkmcnt(2)
	v_mfma_f32_16x16x32_bf16 v[32:35], v[144:147], v[212:215], v[32:35]
	ds_read_b128 v[132:135], v141 offset:10240
	v_mfma_f32_16x16x32_bf16 v[36:39], v[144:147], v[216:219], v[36:39]
	v_mfma_f32_16x16x32_bf16 v[40:43], v[144:147], v[240:243], v[40:43]
	v_mfma_f32_16x16x32_bf16 v[44:47], v[144:147], v[244:247], v[44:47]
	s_waitcnt lgkmcnt(2)
	v_mfma_f32_16x16x32_bf16 v[48:51], v[148:151], v[212:215], v[48:51]
	ds_read_b128 v[144:147], v141 offset:12288
	v_mfma_f32_16x16x32_bf16 v[52:55], v[148:151], v[216:219], v[52:55]
	v_mfma_f32_16x16x32_bf16 v[56:59], v[148:151], v[240:243], v[56:59]
	v_mfma_f32_16x16x32_bf16 v[60:63], v[148:151], v[244:247], v[60:63]
	s_waitcnt lgkmcnt(2)
	v_mfma_f32_16x16x32_bf16 v[64:67], v[128:131], v[212:215], v[64:67]
	ds_read_b128 v[148:151], v141 offset:14336
	v_mfma_f32_16x16x32_bf16 v[68:71], v[128:131], v[216:219], v[68:71]
	v_mfma_f32_16x16x32_bf16 v[72:75], v[128:131], v[240:243], v[72:75]
	v_mfma_f32_16x16x32_bf16 v[76:79], v[128:131], v[244:247], v[76:79]
	s_waitcnt lgkmcnt(2)
	v_mfma_f32_16x16x32_bf16 v[80:83], v[132:135], v[212:215], v[80:83]
	v_mfma_f32_16x16x32_bf16 v[84:87], v[132:135], v[216:219], v[84:87]
	v_mfma_f32_16x16x32_bf16 v[88:91], v[132:135], v[240:243], v[88:91]
	v_mfma_f32_16x16x32_bf16 v[92:95], v[132:135], v[244:247], v[92:95]
	s_waitcnt lgkmcnt(0)
	s_waitcnt vmcnt(0)
	s_barrier
	v_xor_b32_e32 v139, 0x10000, v139
	v_xor_b32_e32 v141, 0x10000, v141
	v_xor_b32_e32 v143, 0x10000, v143
	v_xor_b32_e32 v152, 0x10000, v152
	v_mfma_f32_16x16x32_bf16 v[96:99], v[144:147], v[212:215], v[96:99]
	ds_read_b128 v[128:131], v139
	ds_read_b128 v[132:135], v139 offset:2048
	s_add_u32 m0, s46, 0x10000
	v_mfma_f32_16x16x32_bf16 v[100:103], v[144:147], v[216:219], v[100:103]
	global_load_lds_dwordx4 v248, s[42:43]
	v_mfma_f32_16x16x32_bf16 v[104:107], v[144:147], v[240:243], v[104:107]
	ds_read_b128 v[156:159], v143 offset:32768
	ds_read_b128 v[160:163], v143 offset:34816
	s_add_u32 m0, s46, 0x18000
	v_mfma_f32_16x16x32_bf16 v[108:111], v[144:147], v[244:247], v[108:111]
	global_load_lds_dwordx4 v222, s[44:45]
	v_mfma_f32_16x16x32_bf16 v[112:115], v[148:151], v[212:215], v[112:115]
	ds_read_b128 v[144:147], v139 offset:4096
	s_add_u32 m0, s46, 0x12000
	v_mfma_f32_16x16x32_bf16 v[116:119], v[148:151], v[216:219], v[116:119]
	global_load_lds_dwordx4 v249, s[42:43]
	ds_read_b128 v[164:167], v143 offset:36864
	ds_read_b128 v[202:205], v143 offset:38912
	v_mfma_f32_16x16x32_bf16 v[120:123], v[148:151], v[240:243], v[120:123]
	s_add_u32 m0, s46, 0x1a000
	v_mfma_f32_16x16x32_bf16 v[124:127], v[148:151], v[244:247], v[124:127]
	global_load_lds_dwordx4 v234, s[44:45]
	s_waitcnt lgkmcnt(4)
	v_mfma_f32_16x16x32_bf16 v[0:3], v[128:131], v[156:159], v[0:3]
	ds_read_b128 v[148:151], v139 offset:6144
	s_waitcnt lgkmcnt(4)
	v_mfma_f32_16x16x32_bf16 v[4:7], v[128:131], v[160:163], v[4:7]
	ds_read_b128 v[212:215], v152 offset:32768
	s_waitcnt lgkmcnt(3)
	v_mfma_f32_16x16x32_bf16 v[8:11], v[128:131], v[164:167], v[8:11]
	s_waitcnt lgkmcnt(2)
	v_mfma_f32_16x16x32_bf16 v[12:15], v[128:131], v[202:205], v[12:15]
	v_mfma_f32_16x16x32_bf16 v[16:19], v[132:135], v[156:159], v[16:19]
	ds_read_b128 v[128:131], v139 offset:8192
	v_mfma_f32_16x16x32_bf16 v[20:23], v[132:135], v[160:163], v[20:23]
	ds_read_b128 v[216:219], v152 offset:34816
	v_mfma_f32_16x16x32_bf16 v[24:27], v[132:135], v[164:167], v[24:27]
	v_mfma_f32_16x16x32_bf16 v[28:31], v[132:135], v[202:205], v[28:31]
	v_mfma_f32_16x16x32_bf16 v[32:35], v[144:147], v[156:159], v[32:35]
	ds_read_b128 v[132:135], v139 offset:10240
	v_mfma_f32_16x16x32_bf16 v[36:39], v[144:147], v[160:163], v[36:39]
	ds_read_b128 v[240:243], v152 offset:36864
	v_mfma_f32_16x16x32_bf16 v[40:43], v[144:147], v[164:167], v[40:43]
	s_add_u32 m0, s46, 0x14000
	v_mfma_f32_16x16x32_bf16 v[44:47], v[144:147], v[202:205], v[44:47]
	global_load_lds_dwordx4 v220, s[42:43]
	s_waitcnt lgkmcnt(5)
	v_mfma_f32_16x16x32_bf16 v[48:51], v[148:151], v[156:159], v[48:51]
	ds_read_b128 v[144:147], v139 offset:12288
	v_mfma_f32_16x16x32_bf16 v[52:55], v[148:151], v[160:163], v[52:55]
	ds_read_b128 v[244:247], v152 offset:38912
	v_mfma_f32_16x16x32_bf16 v[56:59], v[148:151], v[164:167], v[56:59]
	s_add_u32 m0, s46, 0x1c000
	v_mfma_f32_16x16x32_bf16 v[60:63], v[148:151], v[202:205], v[60:63]
	global_load_lds_dwordx4 v239, s[44:45]
	s_waitcnt lgkmcnt(5)
	v_mfma_f32_16x16x32_bf16 v[64:67], v[128:131], v[156:159], v[64:67]
	ds_read_b128 v[148:151], v139 offset:14336
	v_mfma_f32_16x16x32_bf16 v[68:71], v[128:131], v[160:163], v[68:71]
	v_mfma_f32_16x16x32_bf16 v[72:75], v[128:131], v[164:167], v[72:75]
	s_add_u32 m0, s46, 0x16000
	v_mfma_f32_16x16x32_bf16 v[76:79], v[128:131], v[202:205], v[76:79]
	global_load_lds_dwordx4 v221, s[42:43]
	s_waitcnt lgkmcnt(4)
	v_mfma_f32_16x16x32_bf16 v[80:83], v[132:135], v[156:159], v[80:83]
	ds_read_b128 v[128:131], v141
	v_mfma_f32_16x16x32_bf16 v[84:87], v[132:135], v[160:163], v[84:87]
	v_mfma_f32_16x16x32_bf16 v[88:91], v[132:135], v[164:167], v[88:91]
	s_add_u32 m0, s46, 0x1e000
	v_mfma_f32_16x16x32_bf16 v[92:95], v[132:135], v[202:205], v[92:95]
	global_load_lds_dwordx4 v252, s[44:45]
	s_add_u32 s42, s42, 0x80
	s_addc_u32 s43, s43, 0
	s_add_u32 s44, s44, 0x80
	s_addc_u32 s45, s45, 0
	s_waitcnt lgkmcnt(3)
	v_mfma_f32_16x16x32_bf16 v[96:99], v[144:147], v[156:159], v[96:99]
	ds_read_b128 v[132:135], v141 offset:2048
	v_mfma_f32_16x16x32_bf16 v[100:103], v[144:147], v[160:163], v[100:103]
	v_mfma_f32_16x16x32_bf16 v[104:107], v[144:147], v[164:167], v[104:107]
	v_mfma_f32_16x16x32_bf16 v[108:111], v[144:147], v[202:205], v[108:111]
	s_waitcnt lgkmcnt(2)
	v_mfma_f32_16x16x32_bf16 v[112:115], v[148:151], v[156:159], v[112:115]
	ds_read_b128 v[144:147], v141 offset:4096
	v_mfma_f32_16x16x32_bf16 v[116:119], v[148:151], v[160:163], v[116:119]
	v_mfma_f32_16x16x32_bf16 v[120:123], v[148:151], v[164:167], v[120:123]
	v_mfma_f32_16x16x32_bf16 v[124:127], v[148:151], v[202:205], v[124:127]
	s_waitcnt lgkmcnt(2)
	v_mfma_f32_16x16x32_bf16 v[0:3], v[128:131], v[212:215], v[0:3]
	ds_read_b128 v[148:151], v141 offset:6144
	v_mfma_f32_16x16x32_bf16 v[4:7], v[128:131], v[216:219], v[4:7]
	v_mfma_f32_16x16x32_bf16 v[8:11], v[128:131], v[240:243], v[8:11]
	v_mfma_f32_16x16x32_bf16 v[12:15], v[128:131], v[244:247], v[12:15]
	s_waitcnt lgkmcnt(2)
	v_mfma_f32_16x16x32_bf16 v[16:19], v[132:135], v[212:215], v[16:19]
	ds_read_b128 v[128:131], v141 offset:8192
	v_mfma_f32_16x16x32_bf16 v[20:23], v[132:135], v[216:219], v[20:23]
	v_mfma_f32_16x16x32_bf16 v[24:27], v[132:135], v[240:243], v[24:27]
	v_mfma_f32_16x16x32_bf16 v[28:31], v[132:135], v[244:247], v[28:31]
	s_waitcnt lgkmcnt(2)
	v_mfma_f32_16x16x32_bf16 v[32:35], v[144:147], v[212:215], v[32:35]
	ds_read_b128 v[132:135], v141 offset:10240
	v_mfma_f32_16x16x32_bf16 v[36:39], v[144:147], v[216:219], v[36:39]
	v_mfma_f32_16x16x32_bf16 v[40:43], v[144:147], v[240:243], v[40:43]
	v_mfma_f32_16x16x32_bf16 v[44:47], v[144:147], v[244:247], v[44:47]
	s_waitcnt lgkmcnt(2)
	v_mfma_f32_16x16x32_bf16 v[48:51], v[148:151], v[212:215], v[48:51]
	ds_read_b128 v[144:147], v141 offset:12288
	v_mfma_f32_16x16x32_bf16 v[52:55], v[148:151], v[216:219], v[52:55]
	v_mfma_f32_16x16x32_bf16 v[56:59], v[148:151], v[240:243], v[56:59]
	v_mfma_f32_16x16x32_bf16 v[60:63], v[148:151], v[244:247], v[60:63]
	s_waitcnt lgkmcnt(2)
	v_mfma_f32_16x16x32_bf16 v[64:67], v[128:131], v[212:215], v[64:67]
	ds_read_b128 v[148:151], v141 offset:14336
	v_mfma_f32_16x16x32_bf16 v[68:71], v[128:131], v[216:219], v[68:71]
	v_mfma_f32_16x16x32_bf16 v[72:75], v[128:131], v[240:243], v[72:75]
	v_mfma_f32_16x16x32_bf16 v[76:79], v[128:131], v[244:247], v[76:79]
	s_waitcnt lgkmcnt(2)
	v_mfma_f32_16x16x32_bf16 v[80:83], v[132:135], v[212:215], v[80:83]
	v_mfma_f32_16x16x32_bf16 v[84:87], v[132:135], v[216:219], v[84:87]
	v_mfma_f32_16x16x32_bf16 v[88:91], v[132:135], v[240:243], v[88:91]
	v_mfma_f32_16x16x32_bf16 v[92:95], v[132:135], v[244:247], v[92:95]
	s_waitcnt lgkmcnt(0)
	s_waitcnt vmcnt(0)
	s_barrier
	v_xor_b32_e32 v139, 0x10000, v139
	v_xor_b32_e32 v141, 0x10000, v141
	v_xor_b32_e32 v143, 0x10000, v143
	v_xor_b32_e32 v152, 0x10000, v152
	v_mfma_f32_16x16x32_bf16 v[96:99], v[144:147], v[212:215], v[96:99]
	ds_read_b128 v[128:131], v139
	ds_read_b128 v[132:135], v139 offset:2048
	s_mov_b32 m0, s46
	v_mfma_f32_16x16x32_bf16 v[100:103], v[144:147], v[216:219], v[100:103]
	global_load_lds_dwordx4 v248, s[42:43]
	v_mfma_f32_16x16x32_bf16 v[104:107], v[144:147], v[240:243], v[104:107]
	ds_read_b128 v[156:159], v143 offset:32768
	ds_read_b128 v[160:163], v143 offset:34816
	s_add_u32 m0, s46, 0x8000
	v_mfma_f32_16x16x32_bf16 v[108:111], v[144:147], v[244:247], v[108:111]
	global_load_lds_dwordx4 v222, s[44:45]
	v_mfma_f32_16x16x32_bf16 v[112:115], v[148:151], v[212:215], v[112:115]
	ds_read_b128 v[144:147], v139 offset:4096
	s_add_u32 m0, s46, 0x2000
	v_mfma_f32_16x16x32_bf16 v[116:119], v[148:151], v[216:219], v[116:119]
	global_load_lds_dwordx4 v249, s[42:43]
	ds_read_b128 v[164:167], v143 offset:36864
	ds_read_b128 v[202:205], v143 offset:38912
	v_mfma_f32_16x16x32_bf16 v[120:123], v[148:151], v[240:243], v[120:123]
	s_add_u32 m0, s46, 0xa000
	v_mfma_f32_16x16x32_bf16 v[124:127], v[148:151], v[244:247], v[124:127]
	global_load_lds_dwordx4 v234, s[44:45]
	s_waitcnt lgkmcnt(4)
	v_mfma_f32_16x16x32_bf16 v[0:3], v[128:131], v[156:159], v[0:3]
	ds_read_b128 v[148:151], v139 offset:6144
	s_waitcnt lgkmcnt(4)
	v_mfma_f32_16x16x32_bf16 v[4:7], v[128:131], v[160:163], v[4:7]
	ds_read_b128 v[212:215], v152 offset:32768
	s_waitcnt lgkmcnt(3)
	v_mfma_f32_16x16x32_bf16 v[8:11], v[128:131], v[164:167], v[8:11]
	s_waitcnt lgkmcnt(2)
	v_mfma_f32_16x16x32_bf16 v[12:15], v[128:131], v[202:205], v[12:15]
	v_mfma_f32_16x16x32_bf16 v[16:19], v[132:135], v[156:159], v[16:19]
	ds_read_b128 v[128:131], v139 offset:8192
	v_mfma_f32_16x16x32_bf16 v[20:23], v[132:135], v[160:163], v[20:23]
	ds_read_b128 v[216:219], v152 offset:34816
	v_mfma_f32_16x16x32_bf16 v[24:27], v[132:135], v[164:167], v[24:27]
	v_mfma_f32_16x16x32_bf16 v[28:31], v[132:135], v[202:205], v[28:31]
	v_mfma_f32_16x16x32_bf16 v[32:35], v[144:147], v[156:159], v[32:35]
	ds_read_b128 v[132:135], v139 offset:10240
	v_mfma_f32_16x16x32_bf16 v[36:39], v[144:147], v[160:163], v[36:39]
	ds_read_b128 v[240:243], v152 offset:36864
	v_mfma_f32_16x16x32_bf16 v[40:43], v[144:147], v[164:167], v[40:43]
	s_add_u32 m0, s46, 0x4000
	v_mfma_f32_16x16x32_bf16 v[44:47], v[144:147], v[202:205], v[44:47]
	global_load_lds_dwordx4 v220, s[42:43]
	s_waitcnt lgkmcnt(5)
	v_mfma_f32_16x16x32_bf16 v[48:51], v[148:151], v[156:159], v[48:51]
	ds_read_b128 v[144:147], v139 offset:12288
	v_mfma_f32_16x16x32_bf16 v[52:55], v[148:151], v[160:163], v[52:55]
	ds_read_b128 v[244:247], v152 offset:38912
	v_mfma_f32_16x16x32_bf16 v[56:59], v[148:151], v[164:167], v[56:59]
	s_add_u32 m0, s46, 0xc000
	v_mfma_f32_16x16x32_bf16 v[60:63], v[148:151], v[202:205], v[60:63]
	global_load_lds_dwordx4 v239, s[44:45]
	s_waitcnt lgkmcnt(5)
	v_mfma_f32_16x16x32_bf16 v[64:67], v[128:131], v[156:159], v[64:67]
	ds_read_b128 v[148:151], v139 offset:14336
	v_mfma_f32_16x16x32_bf16 v[68:71], v[128:131], v[160:163], v[68:71]
	v_mfma_f32_16x16x32_bf16 v[72:75], v[128:131], v[164:167], v[72:75]
	s_add_u32 m0, s46, 0x6000
	v_mfma_f32_16x16x32_bf16 v[76:79], v[128:131], v[202:205], v[76:79]
	global_load_lds_dwordx4 v221, s[42:43]
	s_waitcnt lgkmcnt(4)
	v_mfma_f32_16x16x32_bf16 v[80:83], v[132:135], v[156:159], v[80:83]
	ds_read_b128 v[128:131], v141
	v_mfma_f32_16x16x32_bf16 v[84:87], v[132:135], v[160:163], v[84:87]
	v_mfma_f32_16x16x32_bf16 v[88:91], v[132:135], v[164:167], v[88:91]
	s_add_u32 m0, s46, 0xe000
	v_mfma_f32_16x16x32_bf16 v[92:95], v[132:135], v[202:205], v[92:95]
	global_load_lds_dwordx4 v252, s[44:45]
	s_add_u32 s42, s42, 0x80
	s_addc_u32 s43, s43, 0
	s_add_u32 s44, s44, 0x80
	s_addc_u32 s45, s45, 0
	s_waitcnt lgkmcnt(3)
	v_mfma_f32_16x16x32_bf16 v[96:99], v[144:147], v[156:159], v[96:99]
	ds_read_b128 v[132:135], v141 offset:2048
	v_mfma_f32_16x16x32_bf16 v[100:103], v[144:147], v[160:163], v[100:103]
	v_mfma_f32_16x16x32_bf16 v[104:107], v[144:147], v[164:167], v[104:107]
	v_mfma_f32_16x16x32_bf16 v[108:111], v[144:147], v[202:205], v[108:111]
	s_waitcnt lgkmcnt(2)
	v_mfma_f32_16x16x32_bf16 v[112:115], v[148:151], v[156:159], v[112:115]
	ds_read_b128 v[144:147], v141 offset:4096
	v_mfma_f32_16x16x32_bf16 v[116:119], v[148:151], v[160:163], v[116:119]
	v_mfma_f32_16x16x32_bf16 v[120:123], v[148:151], v[164:167], v[120:123]
	v_mfma_f32_16x16x32_bf16 v[124:127], v[148:151], v[202:205], v[124:127]
	s_waitcnt lgkmcnt(2)
	v_mfma_f32_16x16x32_bf16 v[0:3], v[128:131], v[212:215], v[0:3]
	ds_read_b128 v[148:151], v141 offset:6144
	v_mfma_f32_16x16x32_bf16 v[4:7], v[128:131], v[216:219], v[4:7]
	v_mfma_f32_16x16x32_bf16 v[8:11], v[128:131], v[240:243], v[8:11]
	v_mfma_f32_16x16x32_bf16 v[12:15], v[128:131], v[244:247], v[12:15]
	s_waitcnt lgkmcnt(2)
	v_mfma_f32_16x16x32_bf16 v[16:19], v[132:135], v[212:215], v[16:19]
	ds_read_b128 v[128:131], v141 offset:8192
	v_mfma_f32_16x16x32_bf16 v[20:23], v[132:135], v[216:219], v[20:23]
	v_mfma_f32_16x16x32_bf16 v[24:27], v[132:135], v[240:243], v[24:27]
	v_mfma_f32_16x16x32_bf16 v[28:31], v[132:135], v[244:247], v[28:31]
	s_waitcnt lgkmcnt(2)
	v_mfma_f32_16x16x32_bf16 v[32:35], v[144:147], v[212:215], v[32:35]
	ds_read_b128 v[132:135], v141 offset:10240
	v_mfma_f32_16x16x32_bf16 v[36:39], v[144:147], v[216:219], v[36:39]
	v_mfma_f32_16x16x32_bf16 v[40:43], v[144:147], v[240:243], v[40:43]
	v_mfma_f32_16x16x32_bf16 v[44:47], v[144:147], v[244:247], v[44:47]
	s_waitcnt lgkmcnt(2)
	v_mfma_f32_16x16x32_bf16 v[48:51], v[148:151], v[212:215], v[48:51]
	ds_read_b128 v[144:147], v141 offset:12288
	v_mfma_f32_16x16x32_bf16 v[52:55], v[148:151], v[216:219], v[52:55]
	v_mfma_f32_16x16x32_bf16 v[56:59], v[148:151], v[240:243], v[56:59]
	v_mfma_f32_16x16x32_bf16 v[60:63], v[148:151], v[244:247], v[60:63]
	s_waitcnt lgkmcnt(2)
	v_mfma_f32_16x16x32_bf16 v[64:67], v[128:131], v[212:215], v[64:67]
	ds_read_b128 v[148:151], v141 offset:14336
	v_mfma_f32_16x16x32_bf16 v[68:71], v[128:131], v[216:219], v[68:71]
	v_mfma_f32_16x16x32_bf16 v[72:75], v[128:131], v[240:243], v[72:75]
	v_mfma_f32_16x16x32_bf16 v[76:79], v[128:131], v[244:247], v[76:79]
	s_waitcnt lgkmcnt(2)
	v_mfma_f32_16x16x32_bf16 v[80:83], v[132:135], v[212:215], v[80:83]
	v_mfma_f32_16x16x32_bf16 v[84:87], v[132:135], v[216:219], v[84:87]
	v_mfma_f32_16x16x32_bf16 v[88:91], v[132:135], v[240:243], v[88:91]
	v_mfma_f32_16x16x32_bf16 v[92:95], v[132:135], v[244:247], v[92:95]
	s_waitcnt lgkmcnt(0)
	s_waitcnt vmcnt(0)
	s_barrier
	v_xor_b32_e32 v139, 0x10000, v139
	v_xor_b32_e32 v141, 0x10000, v141
	v_xor_b32_e32 v143, 0x10000, v143
	v_xor_b32_e32 v152, 0x10000, v152
	v_mfma_f32_16x16x32_bf16 v[96:99], v[144:147], v[212:215], v[96:99]
	ds_read_b128 v[128:131], v139
	ds_read_b128 v[132:135], v139 offset:2048
	s_add_u32 m0, s46, 0x10000
	v_mfma_f32_16x16x32_bf16 v[100:103], v[144:147], v[216:219], v[100:103]
	global_load_lds_dwordx4 v248, s[42:43]
	v_mfma_f32_16x16x32_bf16 v[104:107], v[144:147], v[240:243], v[104:107]
	ds_read_b128 v[156:159], v143 offset:32768
	ds_read_b128 v[160:163], v143 offset:34816
	s_add_u32 m0, s46, 0x18000
	v_mfma_f32_16x16x32_bf16 v[108:111], v[144:147], v[244:247], v[108:111]
	global_load_lds_dwordx4 v222, s[44:45]
	v_mfma_f32_16x16x32_bf16 v[112:115], v[148:151], v[212:215], v[112:115]
	ds_read_b128 v[144:147], v139 offset:4096
	s_add_u32 m0, s46, 0x12000
	v_mfma_f32_16x16x32_bf16 v[116:119], v[148:151], v[216:219], v[116:119]
	global_load_lds_dwordx4 v249, s[42:43]
	ds_read_b128 v[164:167], v143 offset:36864
	ds_read_b128 v[202:205], v143 offset:38912
	v_mfma_f32_16x16x32_bf16 v[120:123], v[148:151], v[240:243], v[120:123]
	s_add_u32 m0, s46, 0x1a000
	v_mfma_f32_16x16x32_bf16 v[124:127], v[148:151], v[244:247], v[124:127]
	global_load_lds_dwordx4 v234, s[44:45]
	s_waitcnt lgkmcnt(4)
	v_mfma_f32_16x16x32_bf16 v[0:3], v[128:131], v[156:159], v[0:3]
	ds_read_b128 v[148:151], v139 offset:6144
	s_waitcnt lgkmcnt(4)
	v_mfma_f32_16x16x32_bf16 v[4:7], v[128:131], v[160:163], v[4:7]
	ds_read_b128 v[212:215], v152 offset:32768
	s_waitcnt lgkmcnt(3)
	v_mfma_f32_16x16x32_bf16 v[8:11], v[128:131], v[164:167], v[8:11]
	s_waitcnt lgkmcnt(2)
	v_mfma_f32_16x16x32_bf16 v[12:15], v[128:131], v[202:205], v[12:15]
	v_mfma_f32_16x16x32_bf16 v[16:19], v[132:135], v[156:159], v[16:19]
	ds_read_b128 v[128:131], v139 offset:8192
	v_mfma_f32_16x16x32_bf16 v[20:23], v[132:135], v[160:163], v[20:23]
	ds_read_b128 v[216:219], v152 offset:34816
	v_mfma_f32_16x16x32_bf16 v[24:27], v[132:135], v[164:167], v[24:27]
	v_mfma_f32_16x16x32_bf16 v[28:31], v[132:135], v[202:205], v[28:31]
	v_mfma_f32_16x16x32_bf16 v[32:35], v[144:147], v[156:159], v[32:35]
	ds_read_b128 v[132:135], v139 offset:10240
	v_mfma_f32_16x16x32_bf16 v[36:39], v[144:147], v[160:163], v[36:39]
	ds_read_b128 v[240:243], v152 offset:36864
	v_mfma_f32_16x16x32_bf16 v[40:43], v[144:147], v[164:167], v[40:43]
	s_add_u32 m0, s46, 0x14000
	v_mfma_f32_16x16x32_bf16 v[44:47], v[144:147], v[202:205], v[44:47]
	global_load_lds_dwordx4 v220, s[42:43]
	s_waitcnt lgkmcnt(5)
	v_mfma_f32_16x16x32_bf16 v[48:51], v[148:151], v[156:159], v[48:51]
	ds_read_b128 v[144:147], v139 offset:12288
	v_mfma_f32_16x16x32_bf16 v[52:55], v[148:151], v[160:163], v[52:55]
	ds_read_b128 v[244:247], v152 offset:38912
	v_mfma_f32_16x16x32_bf16 v[56:59], v[148:151], v[164:167], v[56:59]
	s_add_u32 m0, s46, 0x1c000
	v_mfma_f32_16x16x32_bf16 v[60:63], v[148:151], v[202:205], v[60:63]
	global_load_lds_dwordx4 v239, s[44:45]
	s_waitcnt lgkmcnt(5)
	v_mfma_f32_16x16x32_bf16 v[64:67], v[128:131], v[156:159], v[64:67]
	ds_read_b128 v[148:151], v139 offset:14336
	v_mfma_f32_16x16x32_bf16 v[68:71], v[128:131], v[160:163], v[68:71]
	v_mfma_f32_16x16x32_bf16 v[72:75], v[128:131], v[164:167], v[72:75]
	s_add_u32 m0, s46, 0x16000
	v_mfma_f32_16x16x32_bf16 v[76:79], v[128:131], v[202:205], v[76:79]
	global_load_lds_dwordx4 v221, s[42:43]
	s_waitcnt lgkmcnt(4)
	v_mfma_f32_16x16x32_bf16 v[80:83], v[132:135], v[156:159], v[80:83]
	ds_read_b128 v[128:131], v141
	v_mfma_f32_16x16x32_bf16 v[84:87], v[132:135], v[160:163], v[84:87]
	v_mfma_f32_16x16x32_bf16 v[88:91], v[132:135], v[164:167], v[88:91]
	s_add_u32 m0, s46, 0x1e000
	v_mfma_f32_16x16x32_bf16 v[92:95], v[132:135], v[202:205], v[92:95]
	global_load_lds_dwordx4 v252, s[44:45]
	s_add_u32 s42, s42, 0x80
	s_addc_u32 s43, s43, 0
	s_add_u32 s44, s44, 0x80
	s_addc_u32 s45, s45, 0
	s_waitcnt lgkmcnt(3)
	v_mfma_f32_16x16x32_bf16 v[96:99], v[144:147], v[156:159], v[96:99]
	ds_read_b128 v[132:135], v141 offset:2048
	v_mfma_f32_16x16x32_bf16 v[100:103], v[144:147], v[160:163], v[100:103]
	v_mfma_f32_16x16x32_bf16 v[104:107], v[144:147], v[164:167], v[104:107]
	v_mfma_f32_16x16x32_bf16 v[108:111], v[144:147], v[202:205], v[108:111]
	s_waitcnt lgkmcnt(2)
	v_mfma_f32_16x16x32_bf16 v[112:115], v[148:151], v[156:159], v[112:115]
	ds_read_b128 v[144:147], v141 offset:4096
	v_mfma_f32_16x16x32_bf16 v[116:119], v[148:151], v[160:163], v[116:119]
	v_mfma_f32_16x16x32_bf16 v[120:123], v[148:151], v[164:167], v[120:123]
	v_mfma_f32_16x16x32_bf16 v[124:127], v[148:151], v[202:205], v[124:127]
	s_waitcnt lgkmcnt(2)
	v_mfma_f32_16x16x32_bf16 v[0:3], v[128:131], v[212:215], v[0:3]
	ds_read_b128 v[148:151], v141 offset:6144
	v_mfma_f32_16x16x32_bf16 v[4:7], v[128:131], v[216:219], v[4:7]
	v_mfma_f32_16x16x32_bf16 v[8:11], v[128:131], v[240:243], v[8:11]
	v_mfma_f32_16x16x32_bf16 v[12:15], v[128:131], v[244:247], v[12:15]
	s_waitcnt lgkmcnt(2)
	v_mfma_f32_16x16x32_bf16 v[16:19], v[132:135], v[212:215], v[16:19]
	ds_read_b128 v[128:131], v141 offset:8192
	v_mfma_f32_16x16x32_bf16 v[20:23], v[132:135], v[216:219], v[20:23]
	v_mfma_f32_16x16x32_bf16 v[24:27], v[132:135], v[240:243], v[24:27]
	v_mfma_f32_16x16x32_bf16 v[28:31], v[132:135], v[244:247], v[28:31]
	s_waitcnt lgkmcnt(2)
	v_mfma_f32_16x16x32_bf16 v[32:35], v[144:147], v[212:215], v[32:35]
	ds_read_b128 v[132:135], v141 offset:10240
	v_mfma_f32_16x16x32_bf16 v[36:39], v[144:147], v[216:219], v[36:39]
	v_mfma_f32_16x16x32_bf16 v[40:43], v[144:147], v[240:243], v[40:43]
	v_mfma_f32_16x16x32_bf16 v[44:47], v[144:147], v[244:247], v[44:47]
	s_waitcnt lgkmcnt(2)
	v_mfma_f32_16x16x32_bf16 v[48:51], v[148:151], v[212:215], v[48:51]
	ds_read_b128 v[144:147], v141 offset:12288
	v_mfma_f32_16x16x32_bf16 v[52:55], v[148:151], v[216:219], v[52:55]
	v_mfma_f32_16x16x32_bf16 v[56:59], v[148:151], v[240:243], v[56:59]
	v_mfma_f32_16x16x32_bf16 v[60:63], v[148:151], v[244:247], v[60:63]
	s_waitcnt lgkmcnt(2)
	v_mfma_f32_16x16x32_bf16 v[64:67], v[128:131], v[212:215], v[64:67]
	ds_read_b128 v[148:151], v141 offset:14336
	v_mfma_f32_16x16x32_bf16 v[68:71], v[128:131], v[216:219], v[68:71]
	v_mfma_f32_16x16x32_bf16 v[72:75], v[128:131], v[240:243], v[72:75]
	v_mfma_f32_16x16x32_bf16 v[76:79], v[128:131], v[244:247], v[76:79]
	s_waitcnt lgkmcnt(2)
	v_mfma_f32_16x16x32_bf16 v[80:83], v[132:135], v[212:215], v[80:83]
	v_mfma_f32_16x16x32_bf16 v[84:87], v[132:135], v[216:219], v[84:87]
	v_mfma_f32_16x16x32_bf16 v[88:91], v[132:135], v[240:243], v[88:91]
	v_mfma_f32_16x16x32_bf16 v[92:95], v[132:135], v[244:247], v[92:95]
	s_waitcnt lgkmcnt(0)
	s_waitcnt vmcnt(0)
	s_barrier
	v_xor_b32_e32 v139, 0x10000, v139
	v_xor_b32_e32 v141, 0x10000, v141
	v_xor_b32_e32 v143, 0x10000, v143
	v_xor_b32_e32 v152, 0x10000, v152
	v_mfma_f32_16x16x32_bf16 v[96:99], v[144:147], v[212:215], v[96:99]
	ds_read_b128 v[128:131], v139
	ds_read_b128 v[132:135], v139 offset:2048
	s_mov_b32 m0, s46
	v_mfma_f32_16x16x32_bf16 v[100:103], v[144:147], v[216:219], v[100:103]
	global_load_lds_dwordx4 v248, s[42:43]
	v_mfma_f32_16x16x32_bf16 v[104:107], v[144:147], v[240:243], v[104:107]
	ds_read_b128 v[156:159], v143 offset:32768
	ds_read_b128 v[160:163], v143 offset:34816
	s_add_u32 m0, s46, 0x8000
	v_mfma_f32_16x16x32_bf16 v[108:111], v[144:147], v[244:247], v[108:111]
	global_load_lds_dwordx4 v222, s[44:45]
	v_mfma_f32_16x16x32_bf16 v[112:115], v[148:151], v[212:215], v[112:115]
	ds_read_b128 v[144:147], v139 offset:4096
	s_add_u32 m0, s46, 0x2000
	v_mfma_f32_16x16x32_bf16 v[116:119], v[148:151], v[216:219], v[116:119]
	global_load_lds_dwordx4 v249, s[42:43]
	ds_read_b128 v[164:167], v143 offset:36864
	ds_read_b128 v[202:205], v143 offset:38912
	v_mfma_f32_16x16x32_bf16 v[120:123], v[148:151], v[240:243], v[120:123]
	s_add_u32 m0, s46, 0xa000
	v_mfma_f32_16x16x32_bf16 v[124:127], v[148:151], v[244:247], v[124:127]
	global_load_lds_dwordx4 v234, s[44:45]
	s_waitcnt lgkmcnt(4)
	v_mfma_f32_16x16x32_bf16 v[0:3], v[128:131], v[156:159], v[0:3]
	ds_read_b128 v[148:151], v139 offset:6144
	s_waitcnt lgkmcnt(4)
	v_mfma_f32_16x16x32_bf16 v[4:7], v[128:131], v[160:163], v[4:7]
	ds_read_b128 v[212:215], v152 offset:32768
	s_waitcnt lgkmcnt(3)
	v_mfma_f32_16x16x32_bf16 v[8:11], v[128:131], v[164:167], v[8:11]
	s_waitcnt lgkmcnt(2)
	v_mfma_f32_16x16x32_bf16 v[12:15], v[128:131], v[202:205], v[12:15]
	v_mfma_f32_16x16x32_bf16 v[16:19], v[132:135], v[156:159], v[16:19]
	ds_read_b128 v[128:131], v139 offset:8192
	v_mfma_f32_16x16x32_bf16 v[20:23], v[132:135], v[160:163], v[20:23]
	ds_read_b128 v[216:219], v152 offset:34816
	v_mfma_f32_16x16x32_bf16 v[24:27], v[132:135], v[164:167], v[24:27]
	v_mfma_f32_16x16x32_bf16 v[28:31], v[132:135], v[202:205], v[28:31]
	v_mfma_f32_16x16x32_bf16 v[32:35], v[144:147], v[156:159], v[32:35]
	ds_read_b128 v[132:135], v139 offset:10240
	v_mfma_f32_16x16x32_bf16 v[36:39], v[144:147], v[160:163], v[36:39]
	ds_read_b128 v[240:243], v152 offset:36864
	v_mfma_f32_16x16x32_bf16 v[40:43], v[144:147], v[164:167], v[40:43]
	s_add_u32 m0, s46, 0x4000
	v_mfma_f32_16x16x32_bf16 v[44:47], v[144:147], v[202:205], v[44:47]
	global_load_lds_dwordx4 v220, s[42:43]
	s_waitcnt lgkmcnt(5)
	v_mfma_f32_16x16x32_bf16 v[48:51], v[148:151], v[156:159], v[48:51]
	ds_read_b128 v[144:147], v139 offset:12288
	v_mfma_f32_16x16x32_bf16 v[52:55], v[148:151], v[160:163], v[52:55]
	ds_read_b128 v[244:247], v152 offset:38912
	v_mfma_f32_16x16x32_bf16 v[56:59], v[148:151], v[164:167], v[56:59]
	s_add_u32 m0, s46, 0xc000
	v_mfma_f32_16x16x32_bf16 v[60:63], v[148:151], v[202:205], v[60:63]
	global_load_lds_dwordx4 v239, s[44:45]
	s_waitcnt lgkmcnt(5)
	v_mfma_f32_16x16x32_bf16 v[64:67], v[128:131], v[156:159], v[64:67]
	ds_read_b128 v[148:151], v139 offset:14336
	v_mfma_f32_16x16x32_bf16 v[68:71], v[128:131], v[160:163], v[68:71]
	v_mfma_f32_16x16x32_bf16 v[72:75], v[128:131], v[164:167], v[72:75]
	s_add_u32 m0, s46, 0x6000
	v_mfma_f32_16x16x32_bf16 v[76:79], v[128:131], v[202:205], v[76:79]
	global_load_lds_dwordx4 v221, s[42:43]
	s_waitcnt lgkmcnt(4)
	v_mfma_f32_16x16x32_bf16 v[80:83], v[132:135], v[156:159], v[80:83]
	ds_read_b128 v[128:131], v141
	v_mfma_f32_16x16x32_bf16 v[84:87], v[132:135], v[160:163], v[84:87]
	v_mfma_f32_16x16x32_bf16 v[88:91], v[132:135], v[164:167], v[88:91]
	s_add_u32 m0, s46, 0xe000
	v_mfma_f32_16x16x32_bf16 v[92:95], v[132:135], v[202:205], v[92:95]
	global_load_lds_dwordx4 v252, s[44:45]
	s_add_u32 s42, s42, 0x80
	s_addc_u32 s43, s43, 0
	s_add_u32 s44, s44, 0x80
	s_addc_u32 s45, s45, 0
	s_waitcnt lgkmcnt(3)
	v_mfma_f32_16x16x32_bf16 v[96:99], v[144:147], v[156:159], v[96:99]
	ds_read_b128 v[132:135], v141 offset:2048
	v_mfma_f32_16x16x32_bf16 v[100:103], v[144:147], v[160:163], v[100:103]
	v_mfma_f32_16x16x32_bf16 v[104:107], v[144:147], v[164:167], v[104:107]
	v_mfma_f32_16x16x32_bf16 v[108:111], v[144:147], v[202:205], v[108:111]
	s_waitcnt lgkmcnt(2)
	v_mfma_f32_16x16x32_bf16 v[112:115], v[148:151], v[156:159], v[112:115]
	ds_read_b128 v[144:147], v141 offset:4096
	v_mfma_f32_16x16x32_bf16 v[116:119], v[148:151], v[160:163], v[116:119]
	v_mfma_f32_16x16x32_bf16 v[120:123], v[148:151], v[164:167], v[120:123]
	v_mfma_f32_16x16x32_bf16 v[124:127], v[148:151], v[202:205], v[124:127]
	s_waitcnt lgkmcnt(2)
	v_mfma_f32_16x16x32_bf16 v[0:3], v[128:131], v[212:215], v[0:3]
	ds_read_b128 v[148:151], v141 offset:6144
	v_mfma_f32_16x16x32_bf16 v[4:7], v[128:131], v[216:219], v[4:7]
	v_mfma_f32_16x16x32_bf16 v[8:11], v[128:131], v[240:243], v[8:11]
	v_mfma_f32_16x16x32_bf16 v[12:15], v[128:131], v[244:247], v[12:15]
	s_waitcnt lgkmcnt(2)
	v_mfma_f32_16x16x32_bf16 v[16:19], v[132:135], v[212:215], v[16:19]
	ds_read_b128 v[128:131], v141 offset:8192
	v_mfma_f32_16x16x32_bf16 v[20:23], v[132:135], v[216:219], v[20:23]
	v_mfma_f32_16x16x32_bf16 v[24:27], v[132:135], v[240:243], v[24:27]
	v_mfma_f32_16x16x32_bf16 v[28:31], v[132:135], v[244:247], v[28:31]
	s_waitcnt lgkmcnt(2)
	v_mfma_f32_16x16x32_bf16 v[32:35], v[144:147], v[212:215], v[32:35]
	ds_read_b128 v[132:135], v141 offset:10240
	v_mfma_f32_16x16x32_bf16 v[36:39], v[144:147], v[216:219], v[36:39]
	v_mfma_f32_16x16x32_bf16 v[40:43], v[144:147], v[240:243], v[40:43]
	v_mfma_f32_16x16x32_bf16 v[44:47], v[144:147], v[244:247], v[44:47]
	s_waitcnt lgkmcnt(2)
	v_mfma_f32_16x16x32_bf16 v[48:51], v[148:151], v[212:215], v[48:51]
	ds_read_b128 v[144:147], v141 offset:12288
	v_mfma_f32_16x16x32_bf16 v[52:55], v[148:151], v[216:219], v[52:55]
	v_mfma_f32_16x16x32_bf16 v[56:59], v[148:151], v[240:243], v[56:59]
	v_mfma_f32_16x16x32_bf16 v[60:63], v[148:151], v[244:247], v[60:63]
	s_waitcnt lgkmcnt(2)
	v_mfma_f32_16x16x32_bf16 v[64:67], v[128:131], v[212:215], v[64:67]
	ds_read_b128 v[148:151], v141 offset:14336
	v_mfma_f32_16x16x32_bf16 v[68:71], v[128:131], v[216:219], v[68:71]
	v_mfma_f32_16x16x32_bf16 v[72:75], v[128:131], v[240:243], v[72:75]
	v_mfma_f32_16x16x32_bf16 v[76:79], v[128:131], v[244:247], v[76:79]
	s_waitcnt lgkmcnt(2)
	v_mfma_f32_16x16x32_bf16 v[80:83], v[132:135], v[212:215], v[80:83]
	v_mfma_f32_16x16x32_bf16 v[84:87], v[132:135], v[216:219], v[84:87]
	v_mfma_f32_16x16x32_bf16 v[88:91], v[132:135], v[240:243], v[88:91]
	v_mfma_f32_16x16x32_bf16 v[92:95], v[132:135], v[244:247], v[92:95]
	s_waitcnt lgkmcnt(0)
	s_waitcnt vmcnt(0)
	s_barrier
	v_xor_b32_e32 v139, 0x10000, v139
	v_xor_b32_e32 v141, 0x10000, v141
	v_xor_b32_e32 v143, 0x10000, v143
	v_xor_b32_e32 v152, 0x10000, v152
	v_mfma_f32_16x16x32_bf16 v[96:99], v[144:147], v[212:215], v[96:99]
	ds_read_b128 v[128:131], v139
	ds_read_b128 v[132:135], v139 offset:2048
	s_add_u32 m0, s46, 0x10000
	v_mfma_f32_16x16x32_bf16 v[100:103], v[144:147], v[216:219], v[100:103]
	global_load_lds_dwordx4 v248, s[42:43]
	v_mfma_f32_16x16x32_bf16 v[104:107], v[144:147], v[240:243], v[104:107]
	ds_read_b128 v[156:159], v143 offset:32768
	ds_read_b128 v[160:163], v143 offset:34816
	s_add_u32 m0, s46, 0x18000
	v_mfma_f32_16x16x32_bf16 v[108:111], v[144:147], v[244:247], v[108:111]
	global_load_lds_dwordx4 v222, s[44:45]
	v_mfma_f32_16x16x32_bf16 v[112:115], v[148:151], v[212:215], v[112:115]
	ds_read_b128 v[144:147], v139 offset:4096
	s_add_u32 m0, s46, 0x12000
	v_mfma_f32_16x16x32_bf16 v[116:119], v[148:151], v[216:219], v[116:119]
	global_load_lds_dwordx4 v249, s[42:43]
	ds_read_b128 v[164:167], v143 offset:36864
	ds_read_b128 v[202:205], v143 offset:38912
	v_mfma_f32_16x16x32_bf16 v[120:123], v[148:151], v[240:243], v[120:123]
	s_add_u32 m0, s46, 0x1a000
	v_mfma_f32_16x16x32_bf16 v[124:127], v[148:151], v[244:247], v[124:127]
	global_load_lds_dwordx4 v234, s[44:45]
	s_waitcnt lgkmcnt(4)
	v_mfma_f32_16x16x32_bf16 v[0:3], v[128:131], v[156:159], v[0:3]
	ds_read_b128 v[148:151], v139 offset:6144
	s_waitcnt lgkmcnt(4)
	v_mfma_f32_16x16x32_bf16 v[4:7], v[128:131], v[160:163], v[4:7]
	ds_read_b128 v[212:215], v152 offset:32768
	s_waitcnt lgkmcnt(3)
	v_mfma_f32_16x16x32_bf16 v[8:11], v[128:131], v[164:167], v[8:11]
	s_waitcnt lgkmcnt(2)
	v_mfma_f32_16x16x32_bf16 v[12:15], v[128:131], v[202:205], v[12:15]
	v_mfma_f32_16x16x32_bf16 v[16:19], v[132:135], v[156:159], v[16:19]
	ds_read_b128 v[128:131], v139 offset:8192
	v_mfma_f32_16x16x32_bf16 v[20:23], v[132:135], v[160:163], v[20:23]
	ds_read_b128 v[216:219], v152 offset:34816
	v_mfma_f32_16x16x32_bf16 v[24:27], v[132:135], v[164:167], v[24:27]
	v_mfma_f32_16x16x32_bf16 v[28:31], v[132:135], v[202:205], v[28:31]
	v_mfma_f32_16x16x32_bf16 v[32:35], v[144:147], v[156:159], v[32:35]
	ds_read_b128 v[132:135], v139 offset:10240
	v_mfma_f32_16x16x32_bf16 v[36:39], v[144:147], v[160:163], v[36:39]
	ds_read_b128 v[240:243], v152 offset:36864
	v_mfma_f32_16x16x32_bf16 v[40:43], v[144:147], v[164:167], v[40:43]
	s_add_u32 m0, s46, 0x14000
	v_mfma_f32_16x16x32_bf16 v[44:47], v[144:147], v[202:205], v[44:47]
	global_load_lds_dwordx4 v220, s[42:43]
	s_waitcnt lgkmcnt(5)
	v_mfma_f32_16x16x32_bf16 v[48:51], v[148:151], v[156:159], v[48:51]
	ds_read_b128 v[144:147], v139 offset:12288
	v_mfma_f32_16x16x32_bf16 v[52:55], v[148:151], v[160:163], v[52:55]
	ds_read_b128 v[244:247], v152 offset:38912
	v_mfma_f32_16x16x32_bf16 v[56:59], v[148:151], v[164:167], v[56:59]
	s_add_u32 m0, s46, 0x1c000
	v_mfma_f32_16x16x32_bf16 v[60:63], v[148:151], v[202:205], v[60:63]
	global_load_lds_dwordx4 v239, s[44:45]
	s_waitcnt lgkmcnt(5)
	v_mfma_f32_16x16x32_bf16 v[64:67], v[128:131], v[156:159], v[64:67]
	ds_read_b128 v[148:151], v139 offset:14336
	v_mfma_f32_16x16x32_bf16 v[68:71], v[128:131], v[160:163], v[68:71]
	v_mfma_f32_16x16x32_bf16 v[72:75], v[128:131], v[164:167], v[72:75]
	s_add_u32 m0, s46, 0x16000
	v_mfma_f32_16x16x32_bf16 v[76:79], v[128:131], v[202:205], v[76:79]
	global_load_lds_dwordx4 v221, s[42:43]
	s_waitcnt lgkmcnt(4)
	v_mfma_f32_16x16x32_bf16 v[80:83], v[132:135], v[156:159], v[80:83]
	ds_read_b128 v[128:131], v141
	v_mfma_f32_16x16x32_bf16 v[84:87], v[132:135], v[160:163], v[84:87]
	v_mfma_f32_16x16x32_bf16 v[88:91], v[132:135], v[164:167], v[88:91]
	s_add_u32 m0, s46, 0x1e000
	v_mfma_f32_16x16x32_bf16 v[92:95], v[132:135], v[202:205], v[92:95]
	global_load_lds_dwordx4 v252, s[44:45]
	s_add_u32 s42, s42, 0x80
	s_addc_u32 s43, s43, 0
	s_add_u32 s44, s44, 0x80
	s_addc_u32 s45, s45, 0
	s_waitcnt lgkmcnt(3)
	v_mfma_f32_16x16x32_bf16 v[96:99], v[144:147], v[156:159], v[96:99]
	ds_read_b128 v[132:135], v141 offset:2048
	v_mfma_f32_16x16x32_bf16 v[100:103], v[144:147], v[160:163], v[100:103]
	v_mfma_f32_16x16x32_bf16 v[104:107], v[144:147], v[164:167], v[104:107]
	v_mfma_f32_16x16x32_bf16 v[108:111], v[144:147], v[202:205], v[108:111]
	s_waitcnt lgkmcnt(2)
	v_mfma_f32_16x16x32_bf16 v[112:115], v[148:151], v[156:159], v[112:115]
	ds_read_b128 v[144:147], v141 offset:4096
	v_mfma_f32_16x16x32_bf16 v[116:119], v[148:151], v[160:163], v[116:119]
	v_mfma_f32_16x16x32_bf16 v[120:123], v[148:151], v[164:167], v[120:123]
	v_mfma_f32_16x16x32_bf16 v[124:127], v[148:151], v[202:205], v[124:127]
	s_waitcnt lgkmcnt(2)
	v_mfma_f32_16x16x32_bf16 v[0:3], v[128:131], v[212:215], v[0:3]
	ds_read_b128 v[148:151], v141 offset:6144
	v_mfma_f32_16x16x32_bf16 v[4:7], v[128:131], v[216:219], v[4:7]
	v_mfma_f32_16x16x32_bf16 v[8:11], v[128:131], v[240:243], v[8:11]
	v_mfma_f32_16x16x32_bf16 v[12:15], v[128:131], v[244:247], v[12:15]
	s_waitcnt lgkmcnt(2)
	v_mfma_f32_16x16x32_bf16 v[16:19], v[132:135], v[212:215], v[16:19]
	ds_read_b128 v[128:131], v141 offset:8192
	v_mfma_f32_16x16x32_bf16 v[20:23], v[132:135], v[216:219], v[20:23]
	v_mfma_f32_16x16x32_bf16 v[24:27], v[132:135], v[240:243], v[24:27]
	v_mfma_f32_16x16x32_bf16 v[28:31], v[132:135], v[244:247], v[28:31]
	s_waitcnt lgkmcnt(2)
	v_mfma_f32_16x16x32_bf16 v[32:35], v[144:147], v[212:215], v[32:35]
	ds_read_b128 v[132:135], v141 offset:10240
	v_mfma_f32_16x16x32_bf16 v[36:39], v[144:147], v[216:219], v[36:39]
	v_mfma_f32_16x16x32_bf16 v[40:43], v[144:147], v[240:243], v[40:43]
	v_mfma_f32_16x16x32_bf16 v[44:47], v[144:147], v[244:247], v[44:47]
	s_waitcnt lgkmcnt(2)
	v_mfma_f32_16x16x32_bf16 v[48:51], v[148:151], v[212:215], v[48:51]
	ds_read_b128 v[144:147], v141 offset:12288
	v_mfma_f32_16x16x32_bf16 v[52:55], v[148:151], v[216:219], v[52:55]
	v_mfma_f32_16x16x32_bf16 v[56:59], v[148:151], v[240:243], v[56:59]
	v_mfma_f32_16x16x32_bf16 v[60:63], v[148:151], v[244:247], v[60:63]
	s_waitcnt lgkmcnt(2)
	v_mfma_f32_16x16x32_bf16 v[64:67], v[128:131], v[212:215], v[64:67]
	ds_read_b128 v[148:151], v141 offset:14336
	v_mfma_f32_16x16x32_bf16 v[68:71], v[128:131], v[216:219], v[68:71]
	v_mfma_f32_16x16x32_bf16 v[72:75], v[128:131], v[240:243], v[72:75]
	v_mfma_f32_16x16x32_bf16 v[76:79], v[128:131], v[244:247], v[76:79]
	s_waitcnt lgkmcnt(2)
	v_mfma_f32_16x16x32_bf16 v[80:83], v[132:135], v[212:215], v[80:83]
	v_mfma_f32_16x16x32_bf16 v[84:87], v[132:135], v[216:219], v[84:87]
	v_mfma_f32_16x16x32_bf16 v[88:91], v[132:135], v[240:243], v[88:91]
	v_mfma_f32_16x16x32_bf16 v[92:95], v[132:135], v[244:247], v[92:95]
	s_waitcnt lgkmcnt(0)
	s_waitcnt vmcnt(0)
	s_barrier
	v_xor_b32_e32 v139, 0x10000, v139
	v_xor_b32_e32 v141, 0x10000, v141
	v_xor_b32_e32 v143, 0x10000, v143
	v_xor_b32_e32 v152, 0x10000, v152
	v_mfma_f32_16x16x32_bf16 v[96:99], v[144:147], v[212:215], v[96:99]
	ds_read_b128 v[128:131], v139
	ds_read_b128 v[132:135], v139 offset:2048
	v_mfma_f32_16x16x32_bf16 v[100:103], v[144:147], v[216:219], v[100:103]
	v_mfma_f32_16x16x32_bf16 v[104:107], v[144:147], v[240:243], v[104:107]
	ds_read_b128 v[156:159], v143 offset:32768
	ds_read_b128 v[160:163], v143 offset:34816
	v_mfma_f32_16x16x32_bf16 v[108:111], v[144:147], v[244:247], v[108:111]
	v_mfma_f32_16x16x32_bf16 v[112:115], v[148:151], v[212:215], v[112:115]
	ds_read_b128 v[144:147], v139 offset:4096
	v_mfma_f32_16x16x32_bf16 v[116:119], v[148:151], v[216:219], v[116:119]
	ds_read_b128 v[164:167], v143 offset:36864
	ds_read_b128 v[202:205], v143 offset:38912
	v_mfma_f32_16x16x32_bf16 v[120:123], v[148:151], v[240:243], v[120:123]
	v_mfma_f32_16x16x32_bf16 v[124:127], v[148:151], v[244:247], v[124:127]
	s_waitcnt lgkmcnt(4)
	v_mfma_f32_16x16x32_bf16 v[0:3], v[128:131], v[156:159], v[0:3]
	ds_read_b128 v[148:151], v139 offset:6144
	s_waitcnt lgkmcnt(4)
	v_mfma_f32_16x16x32_bf16 v[4:7], v[128:131], v[160:163], v[4:7]
	ds_read_b128 v[212:215], v152 offset:32768
	s_waitcnt lgkmcnt(3)
	v_mfma_f32_16x16x32_bf16 v[8:11], v[128:131], v[164:167], v[8:11]
	s_waitcnt lgkmcnt(2)
	v_mfma_f32_16x16x32_bf16 v[12:15], v[128:131], v[202:205], v[12:15]
	v_mfma_f32_16x16x32_bf16 v[16:19], v[132:135], v[156:159], v[16:19]
	ds_read_b128 v[128:131], v139 offset:8192
	v_mfma_f32_16x16x32_bf16 v[20:23], v[132:135], v[160:163], v[20:23]
	ds_read_b128 v[216:219], v152 offset:34816
	v_mfma_f32_16x16x32_bf16 v[24:27], v[132:135], v[164:167], v[24:27]
	v_mfma_f32_16x16x32_bf16 v[28:31], v[132:135], v[202:205], v[28:31]
	v_mfma_f32_16x16x32_bf16 v[32:35], v[144:147], v[156:159], v[32:35]
	ds_read_b128 v[132:135], v139 offset:10240
	v_mfma_f32_16x16x32_bf16 v[36:39], v[144:147], v[160:163], v[36:39]
	ds_read_b128 v[240:243], v152 offset:36864
	v_mfma_f32_16x16x32_bf16 v[40:43], v[144:147], v[164:167], v[40:43]
	v_mfma_f32_16x16x32_bf16 v[44:47], v[144:147], v[202:205], v[44:47]
	s_waitcnt lgkmcnt(5)
	v_mfma_f32_16x16x32_bf16 v[48:51], v[148:151], v[156:159], v[48:51]
	ds_read_b128 v[144:147], v139 offset:12288
	v_mfma_f32_16x16x32_bf16 v[52:55], v[148:151], v[160:163], v[52:55]
	ds_read_b128 v[244:247], v152 offset:38912
	v_mfma_f32_16x16x32_bf16 v[56:59], v[148:151], v[164:167], v[56:59]
	v_mfma_f32_16x16x32_bf16 v[60:63], v[148:151], v[202:205], v[60:63]
	s_waitcnt lgkmcnt(5)
	v_mfma_f32_16x16x32_bf16 v[64:67], v[128:131], v[156:159], v[64:67]
	ds_read_b128 v[148:151], v139 offset:14336
	v_mfma_f32_16x16x32_bf16 v[68:71], v[128:131], v[160:163], v[68:71]
	v_mfma_f32_16x16x32_bf16 v[72:75], v[128:131], v[164:167], v[72:75]
	v_mfma_f32_16x16x32_bf16 v[76:79], v[128:131], v[202:205], v[76:79]
	s_waitcnt lgkmcnt(4)
	v_mfma_f32_16x16x32_bf16 v[80:83], v[132:135], v[156:159], v[80:83]
	ds_read_b128 v[128:131], v141
	v_mfma_f32_16x16x32_bf16 v[84:87], v[132:135], v[160:163], v[84:87]
	v_mfma_f32_16x16x32_bf16 v[88:91], v[132:135], v[164:167], v[88:91]
	v_mfma_f32_16x16x32_bf16 v[92:95], v[132:135], v[202:205], v[92:95]
	s_waitcnt lgkmcnt(3)
	v_mfma_f32_16x16x32_bf16 v[96:99], v[144:147], v[156:159], v[96:99]
	ds_read_b128 v[132:135], v141 offset:2048
	v_mfma_f32_16x16x32_bf16 v[100:103], v[144:147], v[160:163], v[100:103]
	v_mfma_f32_16x16x32_bf16 v[104:107], v[144:147], v[164:167], v[104:107]
	v_mfma_f32_16x16x32_bf16 v[108:111], v[144:147], v[202:205], v[108:111]
	s_waitcnt lgkmcnt(2)
	v_mfma_f32_16x16x32_bf16 v[112:115], v[148:151], v[156:159], v[112:115]
	ds_read_b128 v[144:147], v141 offset:4096
	v_mfma_f32_16x16x32_bf16 v[116:119], v[148:151], v[160:163], v[116:119]
	v_mfma_f32_16x16x32_bf16 v[120:123], v[148:151], v[164:167], v[120:123]
	v_mfma_f32_16x16x32_bf16 v[124:127], v[148:151], v[202:205], v[124:127]
	s_waitcnt lgkmcnt(2)
	v_mfma_f32_16x16x32_bf16 v[0:3], v[128:131], v[212:215], v[0:3]
	ds_read_b128 v[148:151], v141 offset:6144
	v_mfma_f32_16x16x32_bf16 v[4:7], v[128:131], v[216:219], v[4:7]
	v_mfma_f32_16x16x32_bf16 v[8:11], v[128:131], v[240:243], v[8:11]
	v_mfma_f32_16x16x32_bf16 v[12:15], v[128:131], v[244:247], v[12:15]
	s_waitcnt lgkmcnt(2)
	v_mfma_f32_16x16x32_bf16 v[16:19], v[132:135], v[212:215], v[16:19]
	ds_read_b128 v[128:131], v141 offset:8192
	v_mfma_f32_16x16x32_bf16 v[20:23], v[132:135], v[216:219], v[20:23]
	v_mfma_f32_16x16x32_bf16 v[24:27], v[132:135], v[240:243], v[24:27]
	v_mfma_f32_16x16x32_bf16 v[28:31], v[132:135], v[244:247], v[28:31]
	s_waitcnt lgkmcnt(2)
	v_mfma_f32_16x16x32_bf16 v[32:35], v[144:147], v[212:215], v[32:35]
	ds_read_b128 v[132:135], v141 offset:10240
	v_mfma_f32_16x16x32_bf16 v[36:39], v[144:147], v[216:219], v[36:39]
	v_mfma_f32_16x16x32_bf16 v[40:43], v[144:147], v[240:243], v[40:43]
	v_mfma_f32_16x16x32_bf16 v[44:47], v[144:147], v[244:247], v[44:47]
	s_waitcnt lgkmcnt(2)
	v_mfma_f32_16x16x32_bf16 v[48:51], v[148:151], v[212:215], v[48:51]
	ds_read_b128 v[144:147], v141 offset:12288
	v_mfma_f32_16x16x32_bf16 v[52:55], v[148:151], v[216:219], v[52:55]
	v_mfma_f32_16x16x32_bf16 v[56:59], v[148:151], v[240:243], v[56:59]
	v_mfma_f32_16x16x32_bf16 v[60:63], v[148:151], v[244:247], v[60:63]
	s_waitcnt lgkmcnt(2)
	v_mfma_f32_16x16x32_bf16 v[64:67], v[128:131], v[212:215], v[64:67]
	ds_read_b128 v[148:151], v141 offset:14336
	v_mfma_f32_16x16x32_bf16 v[68:71], v[128:131], v[216:219], v[68:71]
	v_mfma_f32_16x16x32_bf16 v[72:75], v[128:131], v[240:243], v[72:75]
	v_mfma_f32_16x16x32_bf16 v[76:79], v[128:131], v[244:247], v[76:79]
	s_waitcnt lgkmcnt(2)
	v_mfma_f32_16x16x32_bf16 v[80:83], v[132:135], v[212:215], v[80:83]
	v_mfma_f32_16x16x32_bf16 v[84:87], v[132:135], v[216:219], v[84:87]
	v_mfma_f32_16x16x32_bf16 v[88:91], v[132:135], v[240:243], v[88:91]
	v_mfma_f32_16x16x32_bf16 v[92:95], v[132:135], v[244:247], v[92:95]
	s_waitcnt lgkmcnt(0)
	s_waitcnt vmcnt(0)
	s_barrier
	v_xor_b32_e32 v139, 0x10000, v139
	v_xor_b32_e32 v141, 0x10000, v141
	v_xor_b32_e32 v143, 0x10000, v143
	v_xor_b32_e32 v152, 0x10000, v152
	v_mfma_f32_16x16x32_bf16 v[96:99], v[144:147], v[212:215], v[96:99]
	v_mfma_f32_16x16x32_bf16 v[100:103], v[144:147], v[216:219], v[100:103]
	v_mfma_f32_16x16x32_bf16 v[104:107], v[144:147], v[240:243], v[104:107]
	v_mfma_f32_16x16x32_bf16 v[108:111], v[144:147], v[244:247], v[108:111]
	v_mfma_f32_16x16x32_bf16 v[112:115], v[148:151], v[212:215], v[112:115]
	v_mfma_f32_16x16x32_bf16 v[116:119], v[148:151], v[216:219], v[116:119]
	v_mfma_f32_16x16x32_bf16 v[120:123], v[148:151], v[240:243], v[120:123]
	v_mfma_f32_16x16x32_bf16 v[124:127], v[148:151], v[244:247], v[124:127]
	v_mov_b32_e32 v151, 0
	v_add_u32_e32 v128, s10, v169
	v_ashrrev_i32_e32 v130, 7, v128
	v_cmp_lt_i32_e32 vcc, 7, v130
	s_mov_b32 m0, s47
	s_nop 7
	s_nop 3
	s_and_saveexec_b64 s[10:11], vcc
	s_cbranch_execz .LBB0_166
	v_cmp_lt_u32_e32 vcc, 15, v130
	v_mov_b32_e32 v151, 1
	s_and_saveexec_b64 s[24:25], vcc
	s_cbranch_execz .LBB0_165
	v_cmp_lt_u32_e32 vcc, 23, v130
	v_mov_b32_e32 v151, 2
	s_and_saveexec_b64 s[28:29], vcc
	v_cmp_gt_u32_e32 vcc, 40, v130
	s_nop 1
	v_cndmask_b32_e64 v129, 6, 5, vcc
	v_cmp_lt_u32_e32 vcc, 35, v130
	s_nop 1
	v_cndmask_b32_e32 v129, 4, v129, vcc
	v_cmp_lt_u32_e32 vcc, 31, v130
	s_nop 1
	v_cndmask_b32_e32 v151, 3, v129, vcc
	s_or_b64 exec, exec, s[28:29]

.LBB0_175:
	v_mov_b32_e32 v128, v195
	s_nop 0
	v_ashrrev_i32_e32 v129, 8, v128
	v_cmp_eq_u32_e32 vcc, s20, v129
	s_and_saveexec_b64 s[28:29], vcc
	s_cbranch_execz .LBB0_177
	v_bfe_i32 v129, v195, 7, 1
	v_and_b32_e32 v129, 0x10c00, v129
	v_and_b32_e32 v130, 0x4f, v195
	v_lshl_or_b32 v129, v130, 2, v129
	v_bfe_u32 v128, v195, 4, 2
	v_mul_u32_u24_e32 v128, 0x840, v128
	v_add_u32_e32 v128, v128, v129
	v_mov_b32_e32 v129, v128
	v_add_u32_e32 v130, 0x420, v128
	ds_write2_b32 v129, v0, v1 offset1:132
	ds_write2_b32 v130, v2, v3 offset1:132
	ds_write2_b32 v129, v4, v5 offset0:16 offset1:148
	ds_write2_b32 v130, v6, v7 offset0:16 offset1:148
	ds_write2_b32 v129, v8, v9 offset0:32 offset1:164
	ds_write2_b32 v130, v10, v11 offset0:32 offset1:164
	ds_write2_b32 v129, v12, v13 offset0:48 offset1:180
	ds_write2_b32 v130, v14, v15 offset0:48 offset1:180
	v_add_u32_e32 v129, 0x2100, v128
	v_add_u32_e32 v130, 0x2520, v128
	ds_write2_b32 v129, v16, v17 offset1:132
	ds_write2_b32 v130, v18, v19 offset1:132
	ds_write2_b32 v129, v20, v21 offset0:16 offset1:148
	ds_write2_b32 v130, v22, v23 offset0:16 offset1:148
	ds_write2_b32 v129, v24, v25 offset0:32 offset1:164
	ds_write2_b32 v130, v26, v27 offset0:32 offset1:164
	ds_write2_b32 v129, v28, v29 offset0:48 offset1:180
	ds_write2_b32 v130, v30, v31 offset0:48 offset1:180
	v_add_u32_e32 v129, 0x4200, v128
	v_add_u32_e32 v130, 0x4620, v128
	ds_write2_b32 v129, v32, v33 offset1:132
	ds_write2_b32 v130, v34, v35 offset1:132
	ds_write2_b32 v129, v36, v37 offset0:16 offset1:148
	ds_write2_b32 v130, v38, v39 offset0:16 offset1:148
	ds_write2_b32 v129, v40, v41 offset0:32 offset1:164
	ds_write2_b32 v130, v42, v43 offset0:32 offset1:164
	ds_write2_b32 v129, v44, v45 offset0:48 offset1:180
	ds_write2_b32 v130, v46, v47 offset0:48 offset1:180
	v_add_u32_e32 v129, 0x6300, v128
	v_add_u32_e32 v130, 0x6720, v128
	ds_write2_b32 v129, v48, v49 offset1:132
	ds_write2_b32 v130, v50, v51 offset1:132
	ds_write2_b32 v129, v52, v53 offset0:16 offset1:148
	ds_write2_b32 v130, v54, v55 offset0:16 offset1:148
	ds_write2_b32 v129, v56, v57 offset0:32 offset1:164
	ds_write2_b32 v130, v58, v59 offset0:32 offset1:164
	ds_write2_b32 v129, v60, v61 offset0:48 offset1:180
	ds_write2_b32 v130, v62, v63 offset0:48 offset1:180
	v_add_u32_e32 v129, 0x8400, v128
	v_add_u32_e32 v130, 0x8820, v128
	ds_write2_b32 v129, v64, v65 offset1:132
	ds_write2_b32 v130, v66, v67 offset1:132
	ds_write2_b32 v129, v68, v69 offset0:16 offset1:148
	ds_write2_b32 v130, v70, v71 offset0:16 offset1:148
	ds_write2_b32 v129, v72, v73 offset0:32 offset1:164
	ds_write2_b32 v130, v74, v75 offset0:32 offset1:164
	ds_write2_b32 v129, v76, v77 offset0:48 offset1:180
	ds_write2_b32 v130, v78, v79 offset0:48 offset1:180
	v_add_u32_e32 v129, 0xa500, v128
	v_add_u32_e32 v130, 0xa920, v128
	ds_write2_b32 v129, v80, v81 offset1:132
	ds_write2_b32 v130, v82, v83 offset1:132
	ds_write2_b32 v129, v84, v85 offset0:16 offset1:148
	ds_write2_b32 v130, v86, v87 offset0:16 offset1:148
	ds_write2_b32 v129, v88, v89 offset0:32 offset1:164
	ds_write2_b32 v130, v90, v91 offset0:32 offset1:164
	ds_write2_b32 v129, v92, v93 offset0:48 offset1:180
	ds_write2_b32 v130, v94, v95 offset0:48 offset1:180
	v_add_u32_e32 v129, 0xc600, v128
	v_add_u32_e32 v130, 0xca20, v128
	ds_write2_b32 v129, v96, v97 offset1:132
	ds_write2_b32 v130, v98, v99 offset1:132
	ds_write2_b32 v129, v100, v101 offset0:16 offset1:148
	ds_write2_b32 v130, v102, v103 offset0:16 offset1:148
	ds_write2_b32 v129, v104, v105 offset0:32 offset1:164
	ds_write2_b32 v130, v106, v107 offset0:32 offset1:164
	ds_write2_b32 v129, v108, v109 offset0:48 offset1:180
	ds_write2_b32 v130, v110, v111 offset0:48 offset1:180
	v_add_u32_e32 v129, 0xe700, v128
	v_add_u32_e32 v130, 0xeb20, v128
	ds_write2_b32 v129, v112, v113 offset1:132
	ds_write2_b32 v130, v114, v115 offset1:132
	ds_write2_b32 v129, v116, v117 offset0:16 offset1:148
	ds_write2_b32 v130, v118, v119 offset0:16 offset1:148
	ds_write2_b32 v129, v120, v121 offset0:32 offset1:164
	ds_write2_b32 v130, v122, v123 offset0:32 offset1:164
	ds_write2_b32 v129, v124, v125 offset0:48 offset1:180
	ds_write2_b32 v130, v126, v127 offset0:48 offset1:180
